# invhoist + attention K/V tile loads use SGPR base (SALU-advanced) + 32-bit lane offset instead of per-lane 64-bit VALU pointer adds (-16 VALU per 2 tiles per wave)
# speedup vs baseline: 1.0115x; 1.0073x over previous
; __device__ __forceinline__ int v_rd_base(int lane) { return ((lane & 3) << 3) | (((lane >> 2) & 3) << 6) | (((lane >> 4) & 1) << 5) | (((lane >> 5) & 1) << 8); }
; #define SLOAD(i, k0) do { sr_[i].vs0 = *(const GAS bf16x8*)(&Vh[(long)((k0) + sr) * LDK + sc]); sr_[i].vs1 = *(const GAS bf16x8*)(&Vh[(long)((k0) + 32 + sr) * LDK + sc]); \
;     sr_[i].ks0 = *(const GAS bf16x8*)(&Kh[(long)((k0) + kr) * LDK + kc]); } while (0)
; __device__ __forceinline__ void finishSM(f32x16& p0, f32x16& p1, float alpha, float& l_reg, bf16x8& pa0, bf16x8& pa1, bf16x8& pa2, bf16x8& pa3) {
; #pragma unroll
;   for (int r = 0; r < 16; ++r) p1[r] = __builtin_amdgcn_exp2f(p1[r]);
;   float ps = 0;
; #pragma unroll
;   for (int r = 0; r < 16; ++r) ps += p0[r];
; #pragma unroll
;   for (int r = 0; r < 16; ++r) ps += p1[r];
;   { auto rr = __builtin_amdgcn_permlane32_swap(__float_as_uint(ps), __float_as_uint(ps), false, false);
;     ps = __uint_as_float(rr[0]) + __uint_as_float(rr[1]); }
;   l_reg = l_reg * alpha + ps;
;     ...
;   PK4(p0, 0, pa0); PK4(p0, 8, pa1); PK4(p1, 0, pa2); PK4(p1, 8, pa3);
;     ...
; }
; __device__ __forceinline__ void qkt(f32x16& p0, f32x16& p1, const char* Ks, const bf16x8* qr, int r32, int hi) {
;   bf16x8 ka[4], kb[4];
; #pragma unroll
;   for (int d0 = 0; d0 < 4; ++d0) { const int cb = (d0 * 16 + hi * 8) * 2;
;     ka[d0] = *reinterpret_cast<const bf16x8*>(Ks + KSWZ64(r32, cb)); kb[d0] = *reinterpret_cast<const bf16x8*>(Ks + KSWZ64(32 + r32, cb)); }
; template <bool GRPB> __device__ __forceinline__ void attn_pass(const float mbK, const float bmax2, const int pass, float* __restrict__ scr, bf16* __restrict__ mixrow, const float lam, const float* __restrict__ gsub, const float one_m_li, ...
;     ...
;   const int vb0 = (int)(uintptr_t)V_lds + v_rd_base(lane);
;   struct { bf16x8 vs0, vs1, ks0; } sr_[2];
;     ...
;   f32x16 pA0, pA1, pB0, pB1; float mnA, mnB, alA, alB; bf16x8 pa0, pa1, pa2, pa3; constexpr int NT = SEQ / KVBLK;
;   __syncthreads();
;   SLOAD(0, 0); SLOAD(1, KVBLK); asm volatile("s_waitcnt vmcnt(0)" ::: "memory"); SWRITE(0, 0); SWRITE(1, 1);
;   SLOAD(0, 2 * KVBLK); asm volatile("s_waitcnt vmcnt(0)" ::: "memory"); SWRITE(2, 0); __syncthreads();
;   qkt(pA0, pA1, K_lds, qr, r32, hi); partialSM(pA0, pA1, m_reg, mnA, alA, 0, qpos, qw, hi, tb2, cL, cR);
;   int bm1 = 0, b0 = 1, bp1 = 2;
;     ...
;   for (int t = 1; t + 1 < NT; t += 2) {
.LBB0_300:
	v_and_b32_e32 v219, 63, v146
	s_nop 7
	v_lshlrev_b32_e32 v2, 4, v219
	v_lshlrev_b32_e32 v1, 3, v219
	v_and_b32_e32 v2, 0xc0, v2
	v_lshlrev_b32_e32 v3, 1, v219
	v_and_or_b32 v2, v1, 24, v2
	v_and_b32_e32 v3, 32, v3
	v_and_b32_e32 v1, 0x100, v1
	v_and_b32_e32 v4, 15, v146
	v_or3_b32 v231, v2, v3, v1
	v_lshl_add_u64 v[2:3], s[48:49], 0, v[50:51]
	v_lshlrev_b32_e32 v4, 4, v4
	v_mov_b32_e32 v5, v144
	v_lshl_add_u64 v[2:3], v[2:3], 0, v[4:5]
	v_and_b32_e32 v4, 7, v146
	s_cmp_lg_u32 0, -1
	v_exp_f32_e32 v141, v34
	v_exp_f32_e32 v143, v35
	v_exp_f32_e32 v139, v36
	v_exp_f32_e32 v142, v37
	v_exp_f32_e32 v137, v38
	v_exp_f32_e32 v140, v39
	v_exp_f32_e32 v136, v40
	v_exp_f32_e32 v138, v41
	v_exp_f32_e32 v133, v42
	v_exp_f32_e32 v135, v43
	v_exp_f32_e32 v131, v44
	v_exp_f32_e32 v134, v45
	v_exp_f32_e32 v129, v46
	v_exp_f32_e32 v132, v47
	v_exp_f32_e32 v128, v48
	v_exp_f32_e32 v130, v49
	v_lshl_add_u64 v[202:203], s[18:19], 0, v[2:3]
	v_lshl_add_u64 v[2:3], s[48:49], 0, v[52:53]
	v_lshlrev_b32_e32 v4, 4, v4
	s_cselect_b32 s1, 0, 0
	v_lshl_add_u64 v[2:3], v[2:3], 0, v[4:5]
	v_add_u32_e32 v220, s1, v231
	s_lshl_b32 s1, s59, 4
	v_lshl_add_u64 v[204:205], s[18:19], 0, v[2:3]
	v_sub_u32_e32 v2, v200, v54
	s_add_i32 s60, 0, 0x12c00
	v_mov_b32_e32 v221, 0
	s_mov_b32 s64, 1
	s_mov_b32 s0, 0
	v_mov_b32_e32 v1, v0
	v_mov_b32_e32 v66, v0
	v_mov_b32_e32 v67, v0
	v_mov_b32_e32 v68, v0
	v_mov_b32_e32 v69, v0
	v_mov_b32_e32 v70, v0
	v_mov_b32_e32 v71, v0
	v_mov_b32_e32 v72, v0
	s_and_b32 s2, s1, 0x300
	s_sub_i32 s65, 0x7f, s63
	s_mov_b32 s66, 2
	v_add_u32_e32 v240, s60, v2
	s_mov_b32 s67, 1
	v_mov_b32_e32 v2, 0
	v_mov_b32_e32 v3, v221
	v_mov_b32_e32 v4, v221
	v_mov_b32_e32 v5, v221
	v_mov_b32_e32 v6, v221
	v_mov_b32_e32 v7, v221
	v_mov_b32_e32 v8, v221
	v_mov_b32_e32 v9, v221
	v_mov_b32_e32 v10, v221
	v_mov_b32_e32 v11, v221
	v_mov_b32_e32 v12, v221
	v_mov_b32_e32 v13, v221
	v_mov_b32_e32 v14, v221
	v_mov_b32_e32 v15, v221
	v_mov_b32_e32 v16, v221
	v_mov_b32_e32 v17, v221
	v_mov_b32_e32 v18, 0
	v_mov_b32_e32 v19, v221
	v_mov_b32_e32 v20, v221
	v_mov_b32_e32 v21, v221
	v_mov_b32_e32 v22, v221
	v_mov_b32_e32 v23, v221
	v_mov_b32_e32 v24, v221
	v_mov_b32_e32 v25, v221
	v_mov_b32_e32 v26, v221
	v_mov_b32_e32 v27, v221
	v_mov_b32_e32 v28, v221
	v_mov_b32_e32 v29, v221
	v_mov_b32_e32 v30, v221
	v_mov_b32_e32 v31, v221
	v_mov_b32_e32 v32, v221
	v_mov_b32_e32 v33, v221
	v_mov_b32_e32 v34, 0
	v_mov_b32_e32 v35, v221
	v_mov_b32_e32 v36, v221
	v_mov_b32_e32 v37, v221
	v_mov_b32_e32 v38, v221
	v_mov_b32_e32 v39, v221
	v_mov_b32_e32 v40, v221
	v_mov_b32_e32 v41, v221
	v_mov_b32_e32 v42, v221
	v_mov_b32_e32 v43, v221
	v_mov_b32_e32 v44, v221
	v_mov_b32_e32 v45, v221
	v_mov_b32_e32 v46, v221
	v_mov_b32_e32 v47, v221
	v_mov_b32_e32 v48, v221
	v_mov_b32_e32 v49, v221
	v_mov_b32_e32 v50, 0
	v_mov_b32_e32 v51, v221
	v_mov_b32_e32 v52, v221
	v_mov_b32_e32 v53, v221
	v_mov_b32_e32 v54, v221
	v_mov_b32_e32 v55, v221
	v_mov_b32_e32 v56, v221
	v_mov_b32_e32 v57, v221
	v_mov_b32_e32 v58, v221
	v_mov_b32_e32 v59, v221
	v_mov_b32_e32 v60, v221
	v_mov_b32_e32 v61, v221
	v_mov_b32_e32 v62, v221
	v_mov_b32_e32 v63, v221
	v_mov_b32_e32 v64, v221
	v_mov_b32_e32 v65, v221
	v_mov_b32_e32 v75, v0
	v_mov_b32_e32 v74, v0
	v_mov_b32_e32 v73, v0
	v_mov_b32_e32 v78, v0
	v_mov_b32_e32 v79, v0
	v_mov_b32_e32 v76, v0
	v_mov_b32_e32 v77, v0
	s_nop 0
	v_readfirstlane_b32 s70, v202
	v_readfirstlane_b32 s71, v203
	v_readfirstlane_b32 s72, v204
	v_readfirstlane_b32 s73, v205
	s_nop 1
	v_subrev_u32_e32 v202, s70, v202
	v_subrev_u32_e32 v204, s72, v204
	s_add_u32 s70, s70, s2
	s_addc_u32 s71, s71, s3
	s_add_u32 s72, s72, s2
	s_addc_u32 s73, s73, s3
.LBB0_301:
	s_mov_b32 s68, s64
	s_mov_b32 s64, s0
	v_add_f32_e32 v96, 0, v141
	v_add_f32_e32 v96, v143, v96
	v_add_f32_e32 v96, v139, v96
	v_add_f32_e32 v96, v142, v96
	v_add_f32_e32 v96, v137, v96
	v_add_f32_e32 v96, v140, v96
	v_add_f32_e32 v96, v136, v96
	v_add_f32_e32 v96, v138, v96
	v_add_f32_e32 v96, v133, v96
	v_add_f32_e32 v96, v135, v96
	v_add_f32_e32 v96, v131, v96
	v_add_f32_e32 v96, v134, v96
	v_exp_f32_e32 v80, v80
	v_add_f32_e32 v96, v129, v96
	v_exp_f32_e32 v81, v81
	v_add_f32_e32 v96, v132, v96
	v_exp_f32_e32 v82, v82
	v_add_f32_e32 v96, v128, v96
	v_exp_f32_e32 v83, v83
	v_add_f32_e32 v96, v130, v96
	v_exp_f32_e32 v84, v84
	v_add_f32_e32 v96, v80, v96
	v_exp_f32_e32 v85, v85
	v_add_f32_e32 v96, v81, v96
	v_exp_f32_e32 v86, v86
	v_add_f32_e32 v96, v82, v96
	v_exp_f32_e32 v87, v87
	v_add_f32_e32 v96, v83, v96
	v_exp_f32_e32 v88, v88
	v_add_f32_e32 v96, v84, v96
	v_exp_f32_e32 v89, v89
	v_add_f32_e32 v96, v85, v96
	v_exp_f32_e32 v90, v90
	v_add_f32_e32 v96, v86, v96
	v_exp_f32_e32 v91, v91
	v_add_f32_e32 v96, v87, v96
	v_exp_f32_e32 v92, v92
	v_add_f32_e32 v96, v88, v96
	v_exp_f32_e32 v93, v93
	v_add_f32_e32 v96, v89, v96
	v_exp_f32_e32 v94, v94
	v_add_f32_e32 v96, v90, v96
	v_exp_f32_e32 v95, v95
	v_add_f32_e32 v96, v91, v96
	v_add_f32_e32 v96, v92, v96
	v_add_f32_e32 v96, v93, v96
	v_add_f32_e32 v96, v94, v96
	v_add_f32_e32 v241, v95, v96
	v_mov_b32_e32 v242, v241
	v_cvt_pk_bf16_f32 v180, v141, v143
	v_cvt_pk_bf16_f32 v181, v139, v142
	v_cvt_pk_bf16_f32 v182, v137, v140
	v_cvt_pk_bf16_f32 v183, v136, v138
	v_cvt_pk_bf16_f32 v184, v133, v135
	v_cvt_pk_bf16_f32 v185, v131, v134
	v_cvt_pk_bf16_f32 v186, v129, v132
	v_cvt_pk_bf16_f32 v187, v128, v130
	v_cvt_pk_bf16_f32 v188, v80, v81
	v_cvt_pk_bf16_f32 v189, v82, v83
	v_cvt_pk_bf16_f32 v190, v84, v85
	v_cvt_pk_bf16_f32 v191, v86, v87
	v_cvt_pk_bf16_f32 v192, v88, v89
	v_cvt_pk_bf16_f32 v193, v90, v91
	v_cvt_pk_bf16_f32 v194, v92, v93
	v_cvt_pk_bf16_f32 v195, v94, v95
	s_nop 1
	v_permlane32_swap_b32_e32 v241, v242
	v_permlane32_swap_b32_e32 v180, v182
	v_permlane32_swap_b32_e32 v181, v183
	v_permlane32_swap_b32_e32 v184, v186
	v_permlane32_swap_b32_e32 v185, v187
	v_permlane32_swap_b32_e32 v188, v190
	v_permlane32_swap_b32_e32 v189, v191
	v_permlane32_swap_b32_e32 v192, v194
	v_permlane32_swap_b32_e32 v193, v195
	s_lshl_b32 s0, s68, 13
	s_add_i32 s4, s0, 0
	v_add_u32_e32 v84, s4, v224
	v_add_u32_e32 v92, s4, v227
	v_add_u32_e32 v96, s4, v229
	ds_read_b128 v[80:83], v84 offset:49152
	ds_read_b128 v[84:87], v84 offset:53248
	ds_read_b128 v[88:91], v92 offset:49152
	ds_read_b128 v[92:95], v92 offset:53248
	ds_read_b128 v[128:131], v96 offset:49152
	ds_read_b128 v[132:135], v96 offset:53248
	v_add_u32_e32 v96, s4, v230
	ds_read_b128 v[136:139], v96 offset:49152
	ds_read_b128 v[140:143], v96 offset:53248
	s_waitcnt lgkmcnt(0)
; #define SBAR() __builtin_amdgcn_sched_barrier(0)
; __device__ __forceinline__ void partialSM(f32x16& p0, f32x16& p1, float& m_reg, float& mn, float& alpha, int kt0, int qpos, int qw, int hi, const float* tb2, float cL, float cR) {
;   mn = m_reg; alpha = 1.f;
;   const int rel_hi = kt0 + 63 - qw, rel_lo = kt0 - (qw + 31);
;   if (rel_hi <= -91 || rel_lo >= 91) {
;     const float cm = ((rel_hi <= -91) ? cL : cR) - m_reg;
; #pragma unroll
;     for (int r = 0; r < 16; ++r) { p0[r] = fmaf(p0[r], C1, cm); p1[r] = fmaf(p1[r], C1, cm); }
;   } else {
;     const float* tp = tb2 + (kt0 - qpos + 192 + 4 * hi);
; #pragma unroll
;     for (int r4 = 0; r4 < 4; ++r4) {
;       float ta[4], tb[4];
; #pragma unroll
;       for (int i = 0; i < 4; ++i) { ta[i] = tp[8 * r4 + i] - m_reg; tb[i] = tp[32 + 8 * r4 + i] - m_reg; }
; #pragma unroll
;       for (int i = 0; i < 4; ++i) { p0[4 * r4 + i] = fmaf(p0[4 * r4 + i], C1, ta[i]); p1[4 * r4 + i] = fmaf(p1[4 * r4 + i], C1, tb[i]); }
;       asm volatile("" ::: "memory");
;     }
;   }
; #pragma unroll
;   for (int r = 0; r < 16; ++r) p0[r] = __builtin_amdgcn_exp2f(p0[r]);
; }
; __device__ __forceinline__ void finishSM(f32x16& p0, f32x16& p1, float alpha, float& l_reg, bf16x8& pa0, bf16x8& pa1, bf16x8& pa2, bf16x8& pa3) {
; #pragma unroll
;   for (int r = 0; r < 16; ++r) p1[r] = __builtin_amdgcn_exp2f(p1[r]);
;   float ps = 0;
; #pragma unroll
;   for (int r = 0; r < 16; ++r) ps += p0[r];
; #pragma unroll
;   for (int r = 0; r < 16; ++r) ps += p1[r];
;   { auto rr = __builtin_amdgcn_permlane32_swap(__float_as_uint(ps), __float_as_uint(ps), false, false);
;     ps = __uint_as_float(rr[0]) + __uint_as_float(rr[1]); }
;   l_reg = l_reg * alpha + ps;
;     ...
;   PK4(p0, 0, pa0); PK4(p0, 8, pa1); PK4(p1, 0, pa2); PK4(p1, 8, pa3);
;     ...
; }
; __device__ __forceinline__ void qkt(f32x16& p0, f32x16& p1, const char* Ks, const bf16x8* qr, int r32, int hi) {
;   bf16x8 ka[4], kb[4];
; #pragma unroll
;   for (int d0 = 0; d0 < 4; ++d0) { const int cb = (d0 * 16 + hi * 8) * 2;
;     ka[d0] = *reinterpret_cast<const bf16x8*>(Ks + KSWZ64(r32, cb)); kb[d0] = *reinterpret_cast<const bf16x8*>(Ks + KSWZ64(32 + r32, cb)); }
;   asm volatile("s_waitcnt lgkmcnt(0)" ::: "memory"); SBAR();
;   p0 = f32x16{}; p1 = f32x16{};
; #pragma unroll
;   for (int d0 = 0; d0 < 4; ++d0) {
;     p0 = __builtin_amdgcn_mfma_f32_32x32x16_bf16(ka[d0], qr[d0], p0, 0, 0, 0);
	s_waitcnt lgkmcnt(7)
	v_mfma_f32_32x32x16_bf16 v[112:127], v[80:83], v[164:167], 0
	s_waitcnt lgkmcnt(6)
	v_mfma_f32_32x32x16_bf16 v[96:111], v[84:87], v[164:167], 0
	s_waitcnt lgkmcnt(5)
	v_mfma_f32_32x32x16_bf16 v[112:127], v[88:91], v[160:163], v[112:127]
	s_waitcnt lgkmcnt(4)
	v_mfma_f32_32x32x16_bf16 v[96:111], v[92:95], v[160:163], v[96:111]
	s_waitcnt lgkmcnt(3)
	v_mfma_f32_32x32x16_bf16 v[112:127], v[128:131], v[156:159], v[112:127]
	s_waitcnt lgkmcnt(2)
	v_mfma_f32_32x32x16_bf16 v[96:111], v[132:135], v[156:159], v[96:111]
	s_waitcnt lgkmcnt(1)
	v_mfma_f32_32x32x16_bf16 v[112:127], v[136:139], v[152:155], v[112:127]
	s_waitcnt lgkmcnt(0)
	v_mfma_f32_32x32x16_bf16 v[96:111], v[140:143], v[152:155], v[96:111]
	s_add_u32 s74, s70, s15
	s_addc_u32 s75, s71, 0
	global_load_dwordx4 v[168:171], v202, s[74:75] offset:2048
	s_add_u32 s74, s70, 0x18dc0000
	s_addc_u32 s75, s71, 0
	global_load_dwordx4 v[172:175], v202, s[74:75] offset:2048
	s_add_u32 s74, s72, 0x18d80000
	s_addc_u32 s75, s73, 0
	global_load_dwordx4 v[176:179], v204, s[74:75] offset:1024
	s_add_i32 s0, s65, 0xffffff47
	s_cmp_gt_u32 s0, 0xfffffeec
	s_mov_b64 s[0:1], -1
	s_cbranch_scc0 .LBB0_303
	ds_read2_b32 v[80:81], v240 offset1:1
	ds_read2_b32 v[82:83], v240 offset0:32 offset1:33
	ds_read2_b32 v[84:85], v240 offset0:34 offset1:35
	ds_read2_b32 v[86:87], v240 offset0:2 offset1:3
	ds_read2_b32 v[88:89], v240 offset0:8 offset1:9
	ds_read2_b32 v[90:91], v240 offset0:40 offset1:41
	ds_read2_b32 v[92:93], v240 offset0:42 offset1:43
	ds_read2_b32 v[94:95], v240 offset0:10 offset1:11
	ds_read2_b32 v[128:129], v240 offset0:16 offset1:17
	ds_read2_b32 v[244:245], v240 offset0:48 offset1:49
	ds_read2_b32 v[246:247], v240 offset0:50 offset1:51
	ds_read2_b32 v[130:131], v240 offset0:18 offset1:19
	s_waitcnt lgkmcnt(11)
	v_sub_f32_e32 v81, v81, v1
	v_sub_f32_e32 v80, v80, v0
	ds_read2_b32 v[132:133], v240 offset0:24 offset1:25
	ds_read2_b32 v[134:135], v240 offset0:26 offset1:27
	ds_read2_b32 v[248:249], v240 offset0:56 offset1:57
	s_waitcnt lgkmcnt(6)
	v_sub_f32_e32 v137, v129, v75
	v_sub_f32_e32 v136, v128, v72
	v_pk_fma_f32 v[128:129], v[112:113], s[6:7], v[80:81] op_sel_hi:[1,0,1]
	ds_read2_b32 v[80:81], v240 offset0:58 offset1:59
	v_sub_f32_e32 v89, v89, v69
	v_sub_f32_e32 v88, v88, v68
	v_sub_f32_e32 v95, v95, v71
	v_sub_f32_e32 v94, v94, v70
	v_sub_f32_e32 v87, v87, v67
	v_sub_f32_e32 v86, v86, v66
	s_waitcnt lgkmcnt(3)
	v_sub_f32_e32 v141, v133, v79
	v_sub_f32_e32 v140, v132, v78
	s_waitcnt lgkmcnt(2)
	v_sub_f32_e32 v143, v135, v77
	v_sub_f32_e32 v142, v134, v76
	v_sub_f32_e32 v139, v131, v73
	v_sub_f32_e32 v138, v130, v74
	v_pk_fma_f32 v[130:131], v[114:115], s[6:7], v[86:87] op_sel_hi:[1,0,1]
	v_pk_fma_f32 v[134:135], v[118:119], s[6:7], v[94:95] op_sel_hi:[1,0,1]
	v_pk_fma_f32 v[132:133], v[116:117], s[6:7], v[88:89] op_sel_hi:[1,0,1]
	s_waitcnt lgkmcnt(1)
	v_sub_f32_e32 v249, v249, v79
	v_sub_f32_e32 v248, v248, v78
	s_waitcnt lgkmcnt(0)
	v_sub_f32_e32 v95, v81, v77
	v_sub_f32_e32 v94, v80, v76
	v_sub_f32_e32 v89, v245, v75
	v_sub_f32_e32 v88, v244, v72
	v_sub_f32_e32 v245, v247, v73
	v_sub_f32_e32 v244, v246, v74
	v_sub_f32_e32 v91, v91, v69
	v_sub_f32_e32 v90, v90, v68
	v_sub_f32_e32 v87, v93, v71
	v_sub_f32_e32 v86, v92, v70
	v_sub_f32_e32 v81, v83, v1
	v_sub_f32_e32 v80, v82, v0
	v_sub_f32_e32 v83, v85, v67
	v_sub_f32_e32 v82, v84, v66
	v_pk_fma_f32 v[138:139], v[122:123], s[6:7], v[138:139] op_sel_hi:[1,0,1]
	v_pk_fma_f32 v[136:137], v[120:121], s[6:7], v[136:137] op_sel_hi:[1,0,1]
	v_pk_fma_f32 v[142:143], v[126:127], s[6:7], v[142:143] op_sel_hi:[1,0,1]
	v_pk_fma_f32 v[140:141], v[124:125], s[6:7], v[140:141] op_sel_hi:[1,0,1]
	v_pk_fma_f32 v[82:83], v[98:99], s[6:7], v[82:83] op_sel_hi:[1,0,1]
	v_pk_fma_f32 v[80:81], v[96:97], s[6:7], v[80:81] op_sel_hi:[1,0,1]
	v_pk_fma_f32 v[86:87], v[102:103], s[6:7], v[86:87] op_sel_hi:[1,0,1]
	v_pk_fma_f32 v[84:85], v[100:101], s[6:7], v[90:91] op_sel_hi:[1,0,1]
	v_pk_fma_f32 v[90:91], v[106:107], s[6:7], v[244:245] op_sel_hi:[1,0,1]
	v_pk_fma_f32 v[88:89], v[104:105], s[6:7], v[88:89] op_sel_hi:[1,0,1]
	v_pk_fma_f32 v[94:95], v[110:111], s[6:7], v[94:95] op_sel_hi:[1,0,1]
	v_pk_fma_f32 v[92:93], v[108:109], s[6:7], v[248:249] op_sel_hi:[1,0,1]
	s_mov_b64 s[0:1], 0

; #define SBAR() __builtin_amdgcn_sched_barrier(0)
; __device__ __forceinline__ void partialSM(f32x16& p0, f32x16& p1, float& m_reg, float& mn, float& alpha, int kt0, int qpos, int qw, int hi, const float* tb2, float cL, float cR) {
;     ...
; #pragma unroll
;   for (int r = 0; r < 16; ++r) p0[r] = __builtin_amdgcn_exp2f(p0[r]);
; template <int D0> __device__ __forceinline__ void pv_one(f32x16& od, int vb, bf16x8 pa0, bf16x8 pa1, bf16x8 pa2, bf16x8 pa3) {
;   const s16x4 l0 = tr_read<v_rd_off(D0, 0, 0)>(vb), h0 = tr_read<v_rd_off(D0, 0, 1)>(vb), l1 = tr_read<v_rd_off(D0, 1, 0)>(vb), h1 = tr_read<v_rd_off(D0, 1, 1)>(vb);
;   const s16x4 l2 = tr_read<v_rd_off(D0, 2, 0)>(vb), h2 = tr_read<v_rd_off(D0, 2, 1)>(vb), l3 = tr_read<v_rd_off(D0, 3, 0)>(vb), h3 = tr_read<v_rd_off(D0, 3, 1)>(vb);
;   asm volatile("s_waitcnt lgkmcnt(0)" ::: "memory"); SBAR();
;     ...
;   od = __builtin_amdgcn_mfma_f32_32x32x16_bf16(pa0, PK(l0, h0), od, 0, 0, 0);
;   od = __builtin_amdgcn_mfma_f32_32x32x16_bf16(pa1, PK(l1, h1), od, 0, 0, 0);
;   od = __builtin_amdgcn_mfma_f32_32x32x16_bf16(pa2, PK(l2, h2), od, 0, 0, 0);
;   od = __builtin_amdgcn_mfma_f32_32x32x16_bf16(pa3, PK(l3, h3), od, 0, 0, 0);
;     ...
; }
; __device__ __forceinline__ void pv_d0(f32x16* o, int vb, bf16x8 pa0, bf16x8 pa1, bf16x8 pa2, bf16x8 pa3) {
;   pv_one<0>(o[0], vb, pa0, pa1, pa2, pa3); pv_one<1>(o[1], vb, pa0, pa1, pa2, pa3); pv_one<2>(o[2], vb, pa0, pa1, pa2, pa3); pv_one<3>(o[3], vb, pa0, pa1, pa2, pa3);
.LBB0_305:
	v_exp_f32_e32 v112, v128
	v_exp_f32_e32 v113, v129
	v_exp_f32_e32 v114, v130
	v_exp_f32_e32 v115, v131
	v_exp_f32_e32 v116, v132
	v_exp_f32_e32 v117, v133
	v_exp_f32_e32 v118, v134
	v_exp_f32_e32 v119, v135
	v_exp_f32_e32 v120, v136
	v_exp_f32_e32 v121, v137
	v_exp_f32_e32 v122, v138
	v_exp_f32_e32 v123, v139
	v_exp_f32_e32 v124, v140
	v_exp_f32_e32 v125, v141
	v_exp_f32_e32 v126, v142
	v_exp_f32_e32 v127, v143
	s_lshl_b32 s0, s64, 14
	v_add_u32_e32 v128, s0, v220
	ds_read_b64_tr_b16 v[96:97], v128 offset:0
	ds_read_b64_tr_b16 v[98:99], v128 offset:0x800
	ds_read_b64_tr_b16 v[100:101], v128 offset:0x1000
	ds_read_b64_tr_b16 v[102:103], v128 offset:0x1800
	ds_read_b64_tr_b16 v[104:105], v128 offset:0x2000
	ds_read_b64_tr_b16 v[106:107], v128 offset:0x2800
	ds_read_b64_tr_b16 v[108:109], v128 offset:0x3000
	ds_read_b64_tr_b16 v[110:111], v128 offset:0x3800
	s_waitcnt lgkmcnt(0)
	s_nop 0
	v_mfma_f32_32x32x16_bf16 v[2:17], v[180:183], v[96:99], v[2:17]
	ds_read_b64_tr_b16 v[96:97], v128 offset:0x200
	ds_read_b64_tr_b16 v[98:99], v128 offset:0xa00
	v_mfma_f32_32x32x16_bf16 v[2:17], v[184:187], v[100:103], v[2:17]
	ds_read_b64_tr_b16 v[100:101], v128 offset:0x1200
	ds_read_b64_tr_b16 v[102:103], v128 offset:0x1a00
	v_mfma_f32_32x32x16_bf16 v[2:17], v[188:191], v[104:107], v[2:17]
	ds_read_b64_tr_b16 v[104:105], v128 offset:0x2200
	ds_read_b64_tr_b16 v[106:107], v128 offset:0x2a00
	v_mfma_f32_32x32x16_bf16 v[2:17], v[192:195], v[108:111], v[2:17]
	ds_read_b64_tr_b16 v[108:109], v128 offset:0x3200
	ds_read_b64_tr_b16 v[110:111], v128 offset:0x3a00
	s_waitcnt lgkmcnt(0)
	v_mfma_f32_32x32x16_bf16 v[18:33], v[180:183], v[96:99], v[18:33]
	ds_read_b64_tr_b16 v[96:97], v128 offset:0x400
	ds_read_b64_tr_b16 v[98:99], v128 offset:0xc00
	v_mfma_f32_32x32x16_bf16 v[18:33], v[184:187], v[100:103], v[18:33]
	ds_read_b64_tr_b16 v[100:101], v128 offset:0x1400
	ds_read_b64_tr_b16 v[102:103], v128 offset:0x1c00
	v_mfma_f32_32x32x16_bf16 v[18:33], v[188:191], v[104:107], v[18:33]
	ds_read_b64_tr_b16 v[104:105], v128 offset:0x2400
	ds_read_b64_tr_b16 v[106:107], v128 offset:0x2c00
	v_mfma_f32_32x32x16_bf16 v[18:33], v[192:195], v[108:111], v[18:33]
	ds_read_b64_tr_b16 v[108:109], v128 offset:0x3400
	ds_read_b64_tr_b16 v[110:111], v128 offset:0x3c00
	s_waitcnt lgkmcnt(0)
	v_mfma_f32_32x32x16_bf16 v[34:49], v[180:183], v[96:99], v[34:49]
	ds_read_b64_tr_b16 v[96:97], v128 offset:0x600
	ds_read_b64_tr_b16 v[98:99], v128 offset:0xe00
	v_mfma_f32_32x32x16_bf16 v[34:49], v[184:187], v[100:103], v[34:49]
	ds_read_b64_tr_b16 v[100:101], v128 offset:0x1600
	ds_read_b64_tr_b16 v[102:103], v128 offset:0x1e00
	v_mfma_f32_32x32x16_bf16 v[34:49], v[188:191], v[104:107], v[34:49]
	ds_read_b64_tr_b16 v[104:105], v128 offset:0x2600
	ds_read_b64_tr_b16 v[106:107], v128 offset:0x2e00
	v_mfma_f32_32x32x16_bf16 v[34:49], v[192:195], v[108:111], v[34:49]
	ds_read_b64_tr_b16 v[108:109], v128 offset:0x3600
	ds_read_b64_tr_b16 v[110:111], v128 offset:0x3e00
	s_waitcnt lgkmcnt(0)
	v_mfma_f32_32x32x16_bf16 v[50:65], v[180:183], v[96:99], v[50:65]
	s_add_i32 s0, s0, 0
	v_add_u32_e32 v96, s0, v201
	s_barrier
; #define SBAR() __builtin_amdgcn_sched_barrier(0)
; __device__ __forceinline__ void finishSM(f32x16& p0, f32x16& p1, float alpha, float& l_reg, bf16x8& pa0, bf16x8& pa1, bf16x8& pa2, bf16x8& pa3) {
; #pragma unroll
;   for (int r = 0; r < 16; ++r) p1[r] = __builtin_amdgcn_exp2f(p1[r]);
;   float ps = 0;
; #pragma unroll
;   for (int r = 0; r < 16; ++r) ps += p0[r];
; #pragma unroll
;   for (int r = 0; r < 16; ++r) ps += p1[r];
;   { auto rr = __builtin_amdgcn_permlane32_swap(__float_as_uint(ps), __float_as_uint(ps), false, false);
;     ps = __uint_as_float(rr[0]) + __uint_as_float(rr[1]); }
;   l_reg = l_reg * alpha + ps;
;     ...
;   PK4(p0, 0, pa0); PK4(p0, 8, pa1); PK4(p1, 0, pa2); PK4(p1, 8, pa3);
;     ...
; }
; __device__ __forceinline__ void qkt(f32x16& p0, f32x16& p1, const char* Ks, const bf16x8* qr, int r32, int hi) {
;   bf16x8 ka[4], kb[4];
; #pragma unroll
;   for (int d0 = 0; d0 < 4; ++d0) { const int cb = (d0 * 16 + hi * 8) * 2;
;     ka[d0] = *reinterpret_cast<const bf16x8*>(Ks + KSWZ64(r32, cb)); kb[d0] = *reinterpret_cast<const bf16x8*>(Ks + KSWZ64(32 + r32, cb)); }
;   asm volatile("s_waitcnt lgkmcnt(0)" ::: "memory"); SBAR();
;   p0 = f32x16{}; p1 = f32x16{};
; #pragma unroll
;   for (int d0 = 0; d0 < 4; ++d0) {
;     p0 = __builtin_amdgcn_mfma_f32_32x32x16_bf16(ka[d0], qr[d0], p0, 0, 0, 0);
;     p1 = __builtin_amdgcn_mfma_f32_32x32x16_bf16(kb[d0], qr[d0], p1, 0, 0, 0); }
; }
	s_waitcnt vmcnt(2)
	ds_write_b128 v96, v[168:171]
	v_add_u32_e32 v96, s0, v217
	v_mfma_f32_32x32x16_bf16 v[50:65], v[184:187], v[100:103], v[50:65]
	s_waitcnt vmcnt(1)
	ds_write_b128 v96, v[172:175]
	v_lshl_add_u32 v96, s64, 13, v222
	s_waitcnt vmcnt(0)
	ds_write_b128 v96, v[176:179] offset:49152
	v_mfma_f32_32x32x16_bf16 v[50:65], v[188:191], v[104:107], v[50:65]
	v_mfma_f32_32x32x16_bf16 v[50:65], v[192:195], v[108:111], v[50:65]
	v_add_f32_e32 v96, 0, v112
	v_add_f32_e32 v96, v113, v96
	v_add_f32_e32 v96, v114, v96
	v_add_f32_e32 v96, v115, v96
	v_add_f32_e32 v96, v116, v96
	v_add_f32_e32 v96, v117, v96
	v_add_f32_e32 v96, v118, v96
	v_add_f32_e32 v96, v119, v96
	v_add_f32_e32 v96, v120, v96
	v_add_f32_e32 v96, v121, v96
	v_add_f32_e32 v96, v122, v96
	v_add_f32_e32 v96, v123, v96
	v_exp_f32_e32 v80, v80
	v_add_f32_e32 v96, v124, v96
	v_exp_f32_e32 v81, v81
	v_add_f32_e32 v96, v125, v96
	v_exp_f32_e32 v82, v82
	v_add_f32_e32 v96, v126, v96
	v_exp_f32_e32 v83, v83
	v_add_f32_e32 v96, v127, v96
	v_exp_f32_e32 v84, v84
	v_add_f32_e32 v96, v80, v96
	v_exp_f32_e32 v85, v85
	v_add_f32_e32 v96, v81, v96
	v_exp_f32_e32 v86, v86
	v_add_f32_e32 v96, v82, v96
	v_exp_f32_e32 v87, v87
	v_add_f32_e32 v96, v83, v96
	v_exp_f32_e32 v88, v88
	v_add_f32_e32 v96, v84, v96
	v_exp_f32_e32 v89, v89
	v_add_f32_e32 v96, v85, v96
	v_exp_f32_e32 v90, v90
	v_add_f32_e32 v96, v86, v96
	v_exp_f32_e32 v91, v91
	v_add_f32_e32 v96, v87, v96
	v_exp_f32_e32 v92, v92
	v_add_f32_e32 v96, v88, v96
	v_exp_f32_e32 v93, v93
	v_add_f32_e32 v96, v89, v96
	v_exp_f32_e32 v94, v94
	v_add_f32_e32 v96, v90, v96
	v_exp_f32_e32 v95, v95
	v_add_f32_e32 v96, v91, v96
	v_add_f32_e32 v96, v92, v96
	v_add_f32_e32 v96, v93, v96
	v_add_f32_e32 v96, v94, v96
	v_add_f32_e32 v243, v95, v96
	v_mov_b32_e32 v244, v243
	v_cvt_pk_bf16_f32 v180, v112, v113
	v_cvt_pk_bf16_f32 v181, v114, v115
	v_cvt_pk_bf16_f32 v182, v116, v117
	v_cvt_pk_bf16_f32 v183, v118, v119
	v_cvt_pk_bf16_f32 v188, v120, v121
	v_cvt_pk_bf16_f32 v189, v122, v123
	v_cvt_pk_bf16_f32 v190, v124, v125
	v_cvt_pk_bf16_f32 v191, v126, v127
	v_cvt_pk_bf16_f32 v192, v80, v81
	v_cvt_pk_bf16_f32 v193, v82, v83
	v_cvt_pk_bf16_f32 v194, v84, v85
	v_cvt_pk_bf16_f32 v195, v86, v87
	v_cvt_pk_bf16_f32 v184, v88, v89
	v_cvt_pk_bf16_f32 v185, v90, v91
	v_cvt_pk_bf16_f32 v186, v92, v93
	v_cvt_pk_bf16_f32 v187, v94, v95
	s_nop 1
	v_permlane32_swap_b32_e32 v243, v244
	v_permlane32_swap_b32_e32 v180, v182
	v_permlane32_swap_b32_e32 v181, v183
	v_permlane32_swap_b32_e32 v188, v190
	v_permlane32_swap_b32_e32 v189, v191
	v_permlane32_swap_b32_e32 v192, v194
	v_permlane32_swap_b32_e32 v193, v195
	v_permlane32_swap_b32_e32 v184, v186
	v_permlane32_swap_b32_e32 v185, v187
	s_lshl_b32 s0, s66, 13
	s_add_i32 s0, s0, 0
	v_add_u32_e32 v84, s0, v224
	v_add_u32_e32 v92, s0, v227
	v_add_u32_e32 v100, s0, v229
	v_add_u32_e32 v108, s0, v230
	ds_read_b128 v[80:83], v84 offset:49152
	ds_read_b128 v[84:87], v84 offset:53248
	ds_read_b128 v[88:91], v92 offset:49152
	ds_read_b128 v[92:95], v92 offset:53248
	ds_read_b128 v[96:99], v100 offset:49152
	ds_read_b128 v[100:103], v100 offset:53248
	ds_read_b128 v[104:107], v108 offset:49152
	ds_read_b128 v[108:111], v108 offset:53248
	s_waitcnt lgkmcnt(0)
	s_waitcnt lgkmcnt(7)
	v_mfma_f32_32x32x16_bf16 v[128:143], v[80:83], v[164:167], 0
	s_waitcnt lgkmcnt(6)
	v_mfma_f32_32x32x16_bf16 v[112:127], v[84:87], v[164:167], 0
	s_waitcnt lgkmcnt(5)
	v_mfma_f32_32x32x16_bf16 v[128:143], v[88:91], v[160:163], v[128:143]
	s_waitcnt lgkmcnt(4)
	v_mfma_f32_32x32x16_bf16 v[112:127], v[92:95], v[160:163], v[112:127]
	s_waitcnt lgkmcnt(3)
	v_mfma_f32_32x32x16_bf16 v[128:143], v[96:99], v[156:159], v[128:143]
	s_waitcnt lgkmcnt(2)
	v_mfma_f32_32x32x16_bf16 v[112:127], v[100:103], v[156:159], v[112:127]
	s_waitcnt lgkmcnt(1)
	v_mfma_f32_32x32x16_bf16 v[128:143], v[104:107], v[152:155], v[128:143]
	s_waitcnt lgkmcnt(0)
	v_mfma_f32_32x32x16_bf16 v[112:127], v[108:111], v[152:155], v[112:127]
	s_cmp_lt_u32 s67, 61
	s_cselect_b64 s[0:1], -1, 0
	s_cmp_gt_u32 s67, 60
	s_cbranch_scc1 .LBB0_307
	s_add_u32 s74, s70, 0x18e00000
	s_addc_u32 s75, s71, 0
	global_load_dwordx4 v[168:171], v202, s[74:75] offset:2048
	s_add_u32 s74, s70, 0x18e40000
	s_addc_u32 s75, s71, 0
	global_load_dwordx4 v[172:175], v202, s[74:75] offset:2048
	s_add_u32 s74, s72, 0x18e00000
	s_addc_u32 s75, s73, 0
	global_load_dwordx4 v[176:179], v204, s[74:75] offset:1024

; #define SBAR() __builtin_amdgcn_sched_barrier(0)
; #define SLOAD(i, k0) do { sr_[i].vs0 = *(const GAS bf16x8*)(&Vh[(long)((k0) + sr) * LDK + sc]); sr_[i].vs1 = *(const GAS bf16x8*)(&Vh[(long)((k0) + 32 + sr) * LDK + sc]); \
;     sr_[i].ks0 = *(const GAS bf16x8*)(&Kh[(long)((k0) + kr) * LDK + kc]); } while (0)
; #define SWRITE(b, i) do { *(bf16x8*)(V_lds + (b) * SHM_V + vst0) = sr_[i].vs0; *(bf16x8*)(V_lds + (b) * SHM_V + vst1) = sr_[i].vs1; \
;     *(bf16x8*)(K_lds + (b) * SHM_K + kst) = sr_[i].ks0; } while (0)
; template <int D0> __device__ __forceinline__ void pv_one(f32x16& od, int vb, bf16x8 pa0, bf16x8 pa1, bf16x8 pa2, bf16x8 pa3) {
;   const s16x4 l0 = tr_read<v_rd_off(D0, 0, 0)>(vb), h0 = tr_read<v_rd_off(D0, 0, 1)>(vb), l1 = tr_read<v_rd_off(D0, 1, 0)>(vb), h1 = tr_read<v_rd_off(D0, 1, 1)>(vb);
;   const s16x4 l2 = tr_read<v_rd_off(D0, 2, 0)>(vb), h2 = tr_read<v_rd_off(D0, 2, 1)>(vb), l3 = tr_read<v_rd_off(D0, 3, 0)>(vb), h3 = tr_read<v_rd_off(D0, 3, 1)>(vb);
;   asm volatile("s_waitcnt lgkmcnt(0)" ::: "memory"); SBAR();
;     ...
;   od = __builtin_amdgcn_mfma_f32_32x32x16_bf16(pa0, PK(l0, h0), od, 0, 0, 0);
;   od = __builtin_amdgcn_mfma_f32_32x32x16_bf16(pa1, PK(l1, h1), od, 0, 0, 0);
;   od = __builtin_amdgcn_mfma_f32_32x32x16_bf16(pa2, PK(l2, h2), od, 0, 0, 0);
;   od = __builtin_amdgcn_mfma_f32_32x32x16_bf16(pa3, PK(l3, h3), od, 0, 0, 0);
;     ...
; }
; __device__ __forceinline__ void pv_d0(f32x16* o, int vb, bf16x8 pa0, bf16x8 pa1, bf16x8 pa2, bf16x8 pa3) {
;   pv_one<0>(o[0], vb, pa0, pa1, pa2, pa3); pv_one<1>(o[1], vb, pa0, pa1, pa2, pa3); pv_one<2>(o[2], vb, pa0, pa1, pa2, pa3); pv_one<3>(o[3], vb, pa0, pa1, pa2, pa3);
; template <bool GRPB> __device__ __forceinline__ void attn_pass(const float mbK, const float bmax2, const int pass, float* __restrict__ scr, bf16* __restrict__ mixrow, const float lam, const float* __restrict__ gsub, const float one_m_li, ...
;     ...
;   for (int t = 1; t + 1 < NT; t += 2) {
;     HSTEP(pB0, pB1, mnB, alB, pA0, pA1, alA, t * KVBLK, SLOAD(0, (t + 2) * KVBLK));
;     __syncthreads(); SWRITE(bm1, 0);
;     RESC(alB);
;     { const int tmp = bm1; bm1 = b0; b0 = bp1; bp1 = tmp; }
;     HSTEP(pA0, pA1, mnA, alA, pB0, pB1, alB, (t + 1) * KVBLK, if (t + 3 < NT) SLOAD(0, (t + 3) * KVBLK));
;     __syncthreads(); if (t + 3 < NT) SWRITE(bm1, 0);
;     RESC(alA);
;     { const int tmp = bm1; bm1 = b0; b0 = bp1; bp1 = tmp; }
.LBB0_311:
	s_lshl_b32 s8, s68, 14
	v_add_u32_e32 v128, s8, v220
	ds_read_b64_tr_b16 v[112:113], v128 offset:0
	ds_read_b64_tr_b16 v[114:115], v128 offset:0x800
	ds_read_b64_tr_b16 v[116:117], v128 offset:0x1000
	ds_read_b64_tr_b16 v[118:119], v128 offset:0x1800
	ds_read_b64_tr_b16 v[120:121], v128 offset:0x2000
	ds_read_b64_tr_b16 v[122:123], v128 offset:0x2800
	ds_read_b64_tr_b16 v[124:125], v128 offset:0x3000
	ds_read_b64_tr_b16 v[126:127], v128 offset:0x3800
	s_waitcnt lgkmcnt(0)
	s_nop 0
	v_mfma_f32_32x32x16_bf16 v[2:17], v[180:183], v[112:115], v[2:17]
	ds_read_b64_tr_b16 v[112:113], v128 offset:0x200
	ds_read_b64_tr_b16 v[114:115], v128 offset:0xa00
	v_mfma_f32_32x32x16_bf16 v[2:17], v[188:191], v[116:119], v[2:17]
	ds_read_b64_tr_b16 v[116:117], v128 offset:0x1200
	ds_read_b64_tr_b16 v[118:119], v128 offset:0x1a00
	v_mfma_f32_32x32x16_bf16 v[2:17], v[192:195], v[120:123], v[2:17]
	ds_read_b64_tr_b16 v[120:121], v128 offset:0x2200
	ds_read_b64_tr_b16 v[122:123], v128 offset:0x2a00
	v_mfma_f32_32x32x16_bf16 v[2:17], v[184:187], v[124:127], v[2:17]
	ds_read_b64_tr_b16 v[124:125], v128 offset:0x3200
	ds_read_b64_tr_b16 v[126:127], v128 offset:0x3a00
	s_waitcnt lgkmcnt(0)
	v_mfma_f32_32x32x16_bf16 v[18:33], v[180:183], v[112:115], v[18:33]
	ds_read_b64_tr_b16 v[112:113], v128 offset:0x400
	ds_read_b64_tr_b16 v[114:115], v128 offset:0xc00
	v_mfma_f32_32x32x16_bf16 v[18:33], v[188:191], v[116:119], v[18:33]
	ds_read_b64_tr_b16 v[116:117], v128 offset:0x1400
	ds_read_b64_tr_b16 v[118:119], v128 offset:0x1c00
	v_mfma_f32_32x32x16_bf16 v[18:33], v[192:195], v[120:123], v[18:33]
	ds_read_b64_tr_b16 v[120:121], v128 offset:0x2400
	ds_read_b64_tr_b16 v[122:123], v128 offset:0x2c00
	v_mfma_f32_32x32x16_bf16 v[18:33], v[184:187], v[124:127], v[18:33]
	ds_read_b64_tr_b16 v[124:125], v128 offset:0x3400
	ds_read_b64_tr_b16 v[126:127], v128 offset:0x3c00
	s_waitcnt lgkmcnt(0)
	v_mfma_f32_32x32x16_bf16 v[34:49], v[180:183], v[112:115], v[34:49]
	ds_read_b64_tr_b16 v[112:113], v128 offset:0x600
	ds_read_b64_tr_b16 v[114:115], v128 offset:0xe00
	v_mfma_f32_32x32x16_bf16 v[34:49], v[188:191], v[116:119], v[34:49]
	ds_read_b64_tr_b16 v[116:117], v128 offset:0x1600
	ds_read_b64_tr_b16 v[118:119], v128 offset:0x1e00
	v_mfma_f32_32x32x16_bf16 v[34:49], v[192:195], v[120:123], v[34:49]
	ds_read_b64_tr_b16 v[120:121], v128 offset:0x2600
	ds_read_b64_tr_b16 v[122:123], v128 offset:0x2e00
	v_mfma_f32_32x32x16_bf16 v[34:49], v[184:187], v[124:127], v[34:49]
	ds_read_b64_tr_b16 v[124:125], v128 offset:0x3600
	ds_read_b64_tr_b16 v[126:127], v128 offset:0x3e00
	s_waitcnt lgkmcnt(0)
	v_mfma_f32_32x32x16_bf16 v[50:65], v[180:183], v[112:115], v[50:65]
	s_mov_b64 s[54:55], -1
	s_andn2_b64 vcc, exec, s[0:1]
	s_barrier
	v_mfma_f32_32x32x16_bf16 v[50:65], v[188:191], v[116:119], v[50:65]
	v_mfma_f32_32x32x16_bf16 v[50:65], v[192:195], v[120:123], v[50:65]
	v_mfma_f32_32x32x16_bf16 v[50:65], v[184:187], v[124:127], v[50:65]
	s_cbranch_vccnz .LBB0_313
	s_add_i32 s0, s8, 0
	v_add_u32_e32 v114, s0, v201
	s_add_u32 s70, s70, s16
	s_addc_u32 s71, s71, s17
	s_add_u32 s72, s72, s16
	s_addc_u32 s73, s73, s17
	s_addk_i32 s65, 0x80
	v_add_u32_e32 v240, 0x200, v240
	s_add_i32 s67, s67, 2
	s_mov_b64 s[54:55], 0
	v_add_u32_e32 v112, s4, v218
	v_add_u32_e32 v113, s0, v217
	s_waitcnt vmcnt(2)
	ds_write_b128 v114, v[168:171]
	s_waitcnt vmcnt(1)
	ds_write_b128 v113, v[172:175]
	s_waitcnt vmcnt(0)
	ds_write_b128 v112, v[176:179] offset:49152

; __device__ __forceinline__ int v_rd_base(int lane) { return ((lane & 3) << 3) | (((lane >> 2) & 3) << 6) | (((lane >> 4) & 1) << 5) | (((lane >> 5) & 1) << 8); }
; #define SLOAD(i, k0) do { sr_[i].vs0 = *(const GAS bf16x8*)(&Vh[(long)((k0) + sr) * LDK + sc]); sr_[i].vs1 = *(const GAS bf16x8*)(&Vh[(long)((k0) + 32 + sr) * LDK + sc]); \
;     sr_[i].ks0 = *(const GAS bf16x8*)(&Kh[(long)((k0) + kr) * LDK + kc]); } while (0)
; __device__ __forceinline__ void finishSM(f32x16& p0, f32x16& p1, float alpha, float& l_reg, bf16x8& pa0, bf16x8& pa1, bf16x8& pa2, bf16x8& pa3) {
; #pragma unroll
;   for (int r = 0; r < 16; ++r) p1[r] = __builtin_amdgcn_exp2f(p1[r]);
;   float ps = 0;
; #pragma unroll
;   for (int r = 0; r < 16; ++r) ps += p0[r];
; #pragma unroll
;   for (int r = 0; r < 16; ++r) ps += p1[r];
;   { auto rr = __builtin_amdgcn_permlane32_swap(__float_as_uint(ps), __float_as_uint(ps), false, false);
;     ps = __uint_as_float(rr[0]) + __uint_as_float(rr[1]); }
;   l_reg = l_reg * alpha + ps;
;     ...
;   PK4(p0, 0, pa0); PK4(p0, 8, pa1); PK4(p1, 0, pa2); PK4(p1, 8, pa3);
;     ...
; }
; __device__ __forceinline__ void qkt(f32x16& p0, f32x16& p1, const char* Ks, const bf16x8* qr, int r32, int hi) {
;   bf16x8 ka[4], kb[4];
; #pragma unroll
;   for (int d0 = 0; d0 < 4; ++d0) { const int cb = (d0 * 16 + hi * 8) * 2;
;     ka[d0] = *reinterpret_cast<const bf16x8*>(Ks + KSWZ64(r32, cb)); kb[d0] = *reinterpret_cast<const bf16x8*>(Ks + KSWZ64(32 + r32, cb)); }
; template <bool GRPB> __device__ __forceinline__ void attn_pass(const float mbK, const float bmax2, const int pass, float* __restrict__ scr, bf16* __restrict__ mixrow, const float lam, const float* __restrict__ gsub, const float one_m_li, ...
;     ...
;   const int vb0 = (int)(uintptr_t)V_lds + v_rd_base(lane);
;   struct { bf16x8 vs0, vs1, ks0; } sr_[2];
;     ...
;   f32x16 pA0, pA1, pB0, pB1; float mnA, mnB, alA, alB; bf16x8 pa0, pa1, pa2, pa3; constexpr int NT = SEQ / KVBLK;
;   __syncthreads();
;   SLOAD(0, 0); SLOAD(1, KVBLK); asm volatile("s_waitcnt vmcnt(0)" ::: "memory"); SWRITE(0, 0); SWRITE(1, 1);
;   SLOAD(0, 2 * KVBLK); asm volatile("s_waitcnt vmcnt(0)" ::: "memory"); SWRITE(2, 0); __syncthreads();
;   qkt(pA0, pA1, K_lds, qr, r32, hi); partialSM(pA0, pA1, m_reg, mnA, alA, 0, qpos, qw, hi, tb2, cL, cR);
;   int bm1 = 0, b0 = 1, bp1 = 2;
;     ...
;   for (int t = 1; t + 1 < NT; t += 2) {
.LBB0_325:
	v_and_b32_e32 v201, 63, v146
	s_nop 7
	v_lshlrev_b32_e32 v1, 4, v201
	v_lshlrev_b32_e32 v0, 3, v201
	v_and_b32_e32 v1, 0xc0, v1
	v_lshlrev_b32_e32 v2, 1, v201
	v_and_or_b32 v1, v0, 24, v1
	v_and_b32_e32 v2, 32, v2
	v_and_b32_e32 v0, 0x100, v0
	v_or3_b32 v241, v1, v2, v0
	v_and_b32_e32 v2, 15, v146
	v_lshl_add_u64 v[0:1], s[48:49], 0, v[48:49]
	v_lshlrev_b32_e32 v2, 4, v2
	v_mov_b32_e32 v3, v144
	v_lshl_add_u64 v[0:1], v[0:1], 0, v[2:3]
	v_and_b32_e32 v2, 7, v146
	v_exp_f32_e32 v141, v32
	v_exp_f32_e32 v143, v33
	v_exp_f32_e32 v139, v34
	v_exp_f32_e32 v142, v35
	v_exp_f32_e32 v137, v36
	v_exp_f32_e32 v140, v37
	v_exp_f32_e32 v136, v38
	v_exp_f32_e32 v138, v39
	v_exp_f32_e32 v133, v40
	v_exp_f32_e32 v135, v41
	v_exp_f32_e32 v131, v42
	v_exp_f32_e32 v134, v43
	v_exp_f32_e32 v129, v44
	v_exp_f32_e32 v132, v45
	v_exp_f32_e32 v128, v46
	v_exp_f32_e32 v130, v47
	v_lshl_add_u64 v[202:203], s[18:19], 0, v[0:1]
	v_lshl_add_u64 v[0:1], s[48:49], 0, v[50:51]
	v_lshlrev_b32_e32 v2, 4, v2
	s_cmp_lg_u32 0, -1
	v_lshl_add_u64 v[0:1], v[0:1], 0, v[2:3]
	s_cselect_b32 s1, 0, 0
	v_lshl_add_u64 v[204:205], s[18:19], 0, v[0:1]
	v_sub_u32_e32 v0, v200, v52
	v_mov_b32_e32 v220, 0
	s_mov_b32 s65, 1
	s_mov_b32 s0, 0
	v_add_u32_e32 v219, s1, v241
	v_mov_b32_e32 v65, v64
	v_mov_b32_e32 v66, v64
	v_mov_b32_e32 v67, v64
	v_mov_b32_e32 v68, v64
	v_mov_b32_e32 v69, v64
	v_mov_b32_e32 v70, v64
	v_mov_b32_e32 v71, v64
	v_mov_b32_e32 v72, v64
	s_sub_i32 s66, 0x7f, s64
	s_mov_b32 s67, 2
	v_add_u32_e32 v242, s60, v0
	s_mov_b32 s60, 1
	v_mov_b32_e32 v0, 0
	v_mov_b32_e32 v1, v220
	v_mov_b32_e32 v2, v220
	v_mov_b32_e32 v3, v220
	v_mov_b32_e32 v4, v220
	v_mov_b32_e32 v5, v220
	v_mov_b32_e32 v6, v220
	v_mov_b32_e32 v7, v220
	v_mov_b32_e32 v8, v220
	v_mov_b32_e32 v9, v220
	v_mov_b32_e32 v10, v220
	v_mov_b32_e32 v11, v220
	v_mov_b32_e32 v12, v220
	v_mov_b32_e32 v13, v220
	v_mov_b32_e32 v14, v220
	v_mov_b32_e32 v15, v220
	v_mov_b32_e32 v16, 0
	v_mov_b32_e32 v17, v220
	v_mov_b32_e32 v18, v220
	v_mov_b32_e32 v19, v220
	v_mov_b32_e32 v20, v220
	v_mov_b32_e32 v21, v220
	v_mov_b32_e32 v22, v220
	v_mov_b32_e32 v23, v220
	v_mov_b32_e32 v24, v220
	v_mov_b32_e32 v25, v220
	v_mov_b32_e32 v26, v220
	v_mov_b32_e32 v27, v220
	v_mov_b32_e32 v28, v220
	v_mov_b32_e32 v29, v220
	v_mov_b32_e32 v30, v220
	v_mov_b32_e32 v31, v220
	v_mov_b32_e32 v32, 0
	v_mov_b32_e32 v33, v220
	v_mov_b32_e32 v34, v220
	v_mov_b32_e32 v35, v220
	v_mov_b32_e32 v36, v220
	v_mov_b32_e32 v37, v220
	v_mov_b32_e32 v38, v220
	v_mov_b32_e32 v39, v220
	v_mov_b32_e32 v40, v220
	v_mov_b32_e32 v41, v220
	v_mov_b32_e32 v42, v220
	v_mov_b32_e32 v43, v220
	v_mov_b32_e32 v44, v220
	v_mov_b32_e32 v45, v220
	v_mov_b32_e32 v46, v220
	v_mov_b32_e32 v47, v220
	v_mov_b32_e32 v48, 0
	v_mov_b32_e32 v49, v220
	v_mov_b32_e32 v50, v220
	v_mov_b32_e32 v51, v220
	v_mov_b32_e32 v52, v220
	v_mov_b32_e32 v53, v220
	v_mov_b32_e32 v54, v220
	v_mov_b32_e32 v55, v220
	v_mov_b32_e32 v56, v220
	v_mov_b32_e32 v57, v220
	v_mov_b32_e32 v58, v220
	v_mov_b32_e32 v59, v220
	v_mov_b32_e32 v60, v220
	v_mov_b32_e32 v61, v220
	v_mov_b32_e32 v62, v220
	v_mov_b32_e32 v63, v220
	v_mov_b32_e32 v75, v64
	v_mov_b32_e32 v74, v64
	v_mov_b32_e32 v73, v64
	v_mov_b32_e32 v78, v64
	v_mov_b32_e32 v79, v64
	v_mov_b32_e32 v76, v64
	v_mov_b32_e32 v77, v64
	s_nop 0
	v_readfirstlane_b32 s70, v202
	v_readfirstlane_b32 s71, v203
	v_readfirstlane_b32 s72, v204
	v_readfirstlane_b32 s73, v205
	s_nop 1
	v_subrev_u32_e32 v202, s70, v202
	v_subrev_u32_e32 v204, s72, v204
	s_add_u32 s70, s70, s2
	s_addc_u32 s71, s71, s3
	s_add_u32 s72, s72, s2
	s_addc_u32 s73, s73, s3
.LBB0_326:
	s_mov_b32 s68, s65
	s_mov_b32 s65, s0
	v_add_f32_e32 v96, 0, v141
	v_add_f32_e32 v96, v143, v96
	v_add_f32_e32 v96, v139, v96
	v_add_f32_e32 v96, v142, v96
	v_add_f32_e32 v96, v137, v96
	v_add_f32_e32 v96, v140, v96
	v_add_f32_e32 v96, v136, v96
	v_add_f32_e32 v96, v138, v96
	v_add_f32_e32 v96, v133, v96
	v_add_f32_e32 v96, v135, v96
	v_add_f32_e32 v96, v131, v96
	v_add_f32_e32 v96, v134, v96
	v_exp_f32_e32 v80, v80
	v_add_f32_e32 v96, v129, v96
	v_exp_f32_e32 v81, v81
	v_add_f32_e32 v96, v132, v96
	v_exp_f32_e32 v82, v82
	v_add_f32_e32 v96, v128, v96
	v_exp_f32_e32 v83, v83
	v_add_f32_e32 v96, v130, v96
	v_exp_f32_e32 v84, v84
	v_add_f32_e32 v96, v80, v96
	v_exp_f32_e32 v85, v85
	v_add_f32_e32 v96, v81, v96
	v_exp_f32_e32 v86, v86
	v_add_f32_e32 v96, v82, v96
	v_exp_f32_e32 v87, v87
	v_add_f32_e32 v96, v83, v96
	v_exp_f32_e32 v88, v88
	v_add_f32_e32 v96, v84, v96
	v_exp_f32_e32 v89, v89
	v_add_f32_e32 v96, v85, v96
	v_exp_f32_e32 v90, v90
	v_add_f32_e32 v96, v86, v96
	v_exp_f32_e32 v91, v91
	v_add_f32_e32 v96, v87, v96
	v_exp_f32_e32 v92, v92
	v_add_f32_e32 v96, v88, v96
	v_exp_f32_e32 v93, v93
	v_add_f32_e32 v96, v89, v96
	v_exp_f32_e32 v94, v94
	v_add_f32_e32 v96, v90, v96
	v_exp_f32_e32 v95, v95
	v_add_f32_e32 v96, v91, v96
	v_add_f32_e32 v96, v92, v96
	v_add_f32_e32 v96, v93, v96
	v_add_f32_e32 v96, v94, v96
	v_add_f32_e32 v243, v95, v96
	v_mov_b32_e32 v244, v243
	v_cvt_pk_bf16_f32 v180, v141, v143
	v_cvt_pk_bf16_f32 v181, v139, v142
	v_cvt_pk_bf16_f32 v182, v137, v140
	v_cvt_pk_bf16_f32 v183, v136, v138
	v_cvt_pk_bf16_f32 v184, v133, v135
	v_cvt_pk_bf16_f32 v185, v131, v134
	v_cvt_pk_bf16_f32 v186, v129, v132
	v_cvt_pk_bf16_f32 v187, v128, v130
	v_cvt_pk_bf16_f32 v188, v80, v81
	v_cvt_pk_bf16_f32 v189, v82, v83
	v_cvt_pk_bf16_f32 v190, v84, v85
	v_cvt_pk_bf16_f32 v191, v86, v87
	v_cvt_pk_bf16_f32 v192, v88, v89
	v_cvt_pk_bf16_f32 v193, v90, v91
	v_cvt_pk_bf16_f32 v194, v92, v93
	v_cvt_pk_bf16_f32 v195, v94, v95
	s_nop 1
	v_permlane32_swap_b32_e32 v243, v244
	v_permlane32_swap_b32_e32 v180, v182
	v_permlane32_swap_b32_e32 v181, v183
	v_permlane32_swap_b32_e32 v184, v186
	v_permlane32_swap_b32_e32 v185, v187
	v_permlane32_swap_b32_e32 v188, v190
	v_permlane32_swap_b32_e32 v189, v191
	v_permlane32_swap_b32_e32 v192, v194
	v_permlane32_swap_b32_e32 v193, v195
	s_lshl_b32 s0, s68, 13
	s_add_i32 s4, s0, 0
	v_add_u32_e32 v84, s4, v226
	v_add_u32_e32 v92, s4, v229
	v_add_u32_e32 v96, s4, v231
	ds_read_b128 v[80:83], v84 offset:49152
	ds_read_b128 v[84:87], v84 offset:53248
	ds_read_b128 v[88:91], v92 offset:49152
	ds_read_b128 v[92:95], v92 offset:53248
	ds_read_b128 v[128:131], v96 offset:49152
	ds_read_b128 v[132:135], v96 offset:53248
	v_add_u32_e32 v96, s4, v240
	ds_read_b128 v[136:139], v96 offset:49152
	ds_read_b128 v[140:143], v96 offset:53248
	s_waitcnt lgkmcnt(0)
; #define SBAR() __builtin_amdgcn_sched_barrier(0)
; __device__ __forceinline__ void partialSM(f32x16& p0, f32x16& p1, float& m_reg, float& mn, float& alpha, int kt0, int qpos, int qw, int hi, const float* tb2, float cL, float cR) {
;   mn = m_reg; alpha = 1.f;
;   const int rel_hi = kt0 + 63 - qw, rel_lo = kt0 - (qw + 31);
;   if (rel_hi <= -91 || rel_lo >= 91) {
;     const float cm = ((rel_hi <= -91) ? cL : cR) - m_reg;
; #pragma unroll
;     for (int r = 0; r < 16; ++r) { p0[r] = fmaf(p0[r], C1, cm); p1[r] = fmaf(p1[r], C1, cm); }
;   } else {
;     const float* tp = tb2 + (kt0 - qpos + 192 + 4 * hi);
; #pragma unroll
;     for (int r4 = 0; r4 < 4; ++r4) {
;       float ta[4], tb[4];
; #pragma unroll
;       for (int i = 0; i < 4; ++i) { ta[i] = tp[8 * r4 + i] - m_reg; tb[i] = tp[32 + 8 * r4 + i] - m_reg; }
; #pragma unroll
;       for (int i = 0; i < 4; ++i) { p0[4 * r4 + i] = fmaf(p0[4 * r4 + i], C1, ta[i]); p1[4 * r4 + i] = fmaf(p1[4 * r4 + i], C1, tb[i]); }
;       asm volatile("" ::: "memory");
;     }
;   }
; #pragma unroll
;   for (int r = 0; r < 16; ++r) p0[r] = __builtin_amdgcn_exp2f(p0[r]);
; }
; __device__ __forceinline__ void finishSM(f32x16& p0, f32x16& p1, float alpha, float& l_reg, bf16x8& pa0, bf16x8& pa1, bf16x8& pa2, bf16x8& pa3) {
; #pragma unroll
;   for (int r = 0; r < 16; ++r) p1[r] = __builtin_amdgcn_exp2f(p1[r]);
;   float ps = 0;
; #pragma unroll
;   for (int r = 0; r < 16; ++r) ps += p0[r];
; #pragma unroll
;   for (int r = 0; r < 16; ++r) ps += p1[r];
;   { auto rr = __builtin_amdgcn_permlane32_swap(__float_as_uint(ps), __float_as_uint(ps), false, false);
;     ps = __uint_as_float(rr[0]) + __uint_as_float(rr[1]); }
;   l_reg = l_reg * alpha + ps;
;     ...
;   PK4(p0, 0, pa0); PK4(p0, 8, pa1); PK4(p1, 0, pa2); PK4(p1, 8, pa3);
;     ...
; }
; __device__ __forceinline__ void qkt(f32x16& p0, f32x16& p1, const char* Ks, const bf16x8* qr, int r32, int hi) {
;   bf16x8 ka[4], kb[4];
; #pragma unroll
;   for (int d0 = 0; d0 < 4; ++d0) { const int cb = (d0 * 16 + hi * 8) * 2;
;     ka[d0] = *reinterpret_cast<const bf16x8*>(Ks + KSWZ64(r32, cb)); kb[d0] = *reinterpret_cast<const bf16x8*>(Ks + KSWZ64(32 + r32, cb)); }
;   asm volatile("s_waitcnt lgkmcnt(0)" ::: "memory"); SBAR();
;   p0 = f32x16{}; p1 = f32x16{};
; #pragma unroll
;   for (int d0 = 0; d0 < 4; ++d0) {
;     p0 = __builtin_amdgcn_mfma_f32_32x32x16_bf16(ka[d0], qr[d0], p0, 0, 0, 0);
	s_waitcnt lgkmcnt(7)
	v_mfma_f32_32x32x16_bf16 v[112:127], v[80:83], v[164:167], 0
	s_waitcnt lgkmcnt(6)
	v_mfma_f32_32x32x16_bf16 v[96:111], v[84:87], v[164:167], 0
	s_waitcnt lgkmcnt(5)
	v_mfma_f32_32x32x16_bf16 v[112:127], v[88:91], v[160:163], v[112:127]
	s_waitcnt lgkmcnt(4)
	v_mfma_f32_32x32x16_bf16 v[96:111], v[92:95], v[160:163], v[96:111]
	s_waitcnt lgkmcnt(3)
	v_mfma_f32_32x32x16_bf16 v[112:127], v[128:131], v[152:155], v[112:127]
	s_waitcnt lgkmcnt(2)
	v_mfma_f32_32x32x16_bf16 v[96:111], v[132:135], v[152:155], v[96:111]
	s_waitcnt lgkmcnt(1)
	v_mfma_f32_32x32x16_bf16 v[112:127], v[136:139], v[156:159], v[112:127]
	s_waitcnt lgkmcnt(0)
	v_mfma_f32_32x32x16_bf16 v[96:111], v[140:143], v[156:159], v[96:111]
	s_add_u32 s74, s70, s15
	s_addc_u32 s75, s71, 0
	global_load_dwordx4 v[168:171], v202, s[74:75] offset:2048
	s_add_u32 s74, s70, 0x18dc0000
	s_addc_u32 s75, s71, 0
	global_load_dwordx4 v[172:175], v202, s[74:75] offset:2048
	s_add_u32 s74, s72, 0x18d80000
	s_addc_u32 s75, s73, 0
	global_load_dwordx4 v[176:179], v204, s[74:75] offset:1152
	s_add_i32 s0, s66, 0xffffff47
	s_cmp_gt_u32 s0, 0xfffffeec
	s_mov_b64 s[0:1], -1
	s_cbranch_scc0 .LBB0_328
	ds_read2_b32 v[80:81], v242 offset1:1
	ds_read2_b32 v[82:83], v242 offset0:32 offset1:33
	ds_read2_b32 v[84:85], v242 offset0:34 offset1:35
	ds_read2_b32 v[86:87], v242 offset0:2 offset1:3
	ds_read2_b32 v[88:89], v242 offset0:8 offset1:9
	ds_read2_b32 v[90:91], v242 offset0:40 offset1:41
	ds_read2_b32 v[92:93], v242 offset0:42 offset1:43
	ds_read2_b32 v[94:95], v242 offset0:10 offset1:11
	ds_read2_b32 v[128:129], v242 offset0:16 offset1:17
	ds_read2_b32 v[246:247], v242 offset0:48 offset1:49
	ds_read2_b32 v[248:249], v242 offset0:50 offset1:51
	ds_read2_b32 v[130:131], v242 offset0:18 offset1:19
	s_waitcnt lgkmcnt(11)
	v_sub_f32_e32 v81, v81, v65
	v_sub_f32_e32 v80, v80, v64
	ds_read2_b32 v[132:133], v242 offset0:24 offset1:25
	ds_read2_b32 v[134:135], v242 offset0:26 offset1:27
	ds_read2_b32 v[250:251], v242 offset0:56 offset1:57
	s_waitcnt lgkmcnt(6)
	v_sub_f32_e32 v137, v129, v75
	v_sub_f32_e32 v136, v128, v72
	v_pk_fma_f32 v[128:129], v[112:113], s[6:7], v[80:81] op_sel_hi:[1,0,1]
	ds_read2_b32 v[80:81], v242 offset0:58 offset1:59
	v_sub_f32_e32 v89, v89, v69
	v_sub_f32_e32 v88, v88, v68
	v_sub_f32_e32 v95, v95, v71
	v_sub_f32_e32 v94, v94, v70
	v_sub_f32_e32 v87, v87, v67
	v_sub_f32_e32 v86, v86, v66
	s_waitcnt lgkmcnt(3)
	v_sub_f32_e32 v141, v133, v79
	v_sub_f32_e32 v140, v132, v78
	s_waitcnt lgkmcnt(2)
	v_sub_f32_e32 v143, v135, v77
	v_sub_f32_e32 v142, v134, v76
	v_sub_f32_e32 v139, v131, v73
	v_sub_f32_e32 v138, v130, v74
	v_pk_fma_f32 v[130:131], v[114:115], s[6:7], v[86:87] op_sel_hi:[1,0,1]
	v_pk_fma_f32 v[134:135], v[118:119], s[6:7], v[94:95] op_sel_hi:[1,0,1]
	v_pk_fma_f32 v[132:133], v[116:117], s[6:7], v[88:89] op_sel_hi:[1,0,1]
	s_waitcnt lgkmcnt(1)
	v_sub_f32_e32 v251, v251, v79
	v_sub_f32_e32 v250, v250, v78
	s_waitcnt lgkmcnt(0)
	v_sub_f32_e32 v95, v81, v77
	v_sub_f32_e32 v94, v80, v76
	v_sub_f32_e32 v89, v247, v75
	v_sub_f32_e32 v88, v246, v72
	v_sub_f32_e32 v247, v249, v73
	v_sub_f32_e32 v246, v248, v74
	v_sub_f32_e32 v91, v91, v69
	v_sub_f32_e32 v90, v90, v68
	v_sub_f32_e32 v87, v93, v71
	v_sub_f32_e32 v86, v92, v70
	v_sub_f32_e32 v81, v83, v65
	v_sub_f32_e32 v80, v82, v64
	v_sub_f32_e32 v83, v85, v67
	v_sub_f32_e32 v82, v84, v66
	v_pk_fma_f32 v[138:139], v[122:123], s[6:7], v[138:139] op_sel_hi:[1,0,1]
	v_pk_fma_f32 v[136:137], v[120:121], s[6:7], v[136:137] op_sel_hi:[1,0,1]
	v_pk_fma_f32 v[142:143], v[126:127], s[6:7], v[142:143] op_sel_hi:[1,0,1]
	v_pk_fma_f32 v[140:141], v[124:125], s[6:7], v[140:141] op_sel_hi:[1,0,1]
	v_pk_fma_f32 v[82:83], v[98:99], s[6:7], v[82:83] op_sel_hi:[1,0,1]
	v_pk_fma_f32 v[80:81], v[96:97], s[6:7], v[80:81] op_sel_hi:[1,0,1]
	v_pk_fma_f32 v[86:87], v[102:103], s[6:7], v[86:87] op_sel_hi:[1,0,1]
	v_pk_fma_f32 v[84:85], v[100:101], s[6:7], v[90:91] op_sel_hi:[1,0,1]
	v_pk_fma_f32 v[90:91], v[106:107], s[6:7], v[246:247] op_sel_hi:[1,0,1]
	v_pk_fma_f32 v[88:89], v[104:105], s[6:7], v[88:89] op_sel_hi:[1,0,1]
	v_pk_fma_f32 v[94:95], v[110:111], s[6:7], v[94:95] op_sel_hi:[1,0,1]
	v_pk_fma_f32 v[92:93], v[108:109], s[6:7], v[250:251] op_sel_hi:[1,0,1]
	s_mov_b64 s[0:1], 0

; #define SBAR() __builtin_amdgcn_sched_barrier(0)
; __device__ __forceinline__ void partialSM(f32x16& p0, f32x16& p1, float& m_reg, float& mn, float& alpha, int kt0, int qpos, int qw, int hi, const float* tb2, float cL, float cR) {
;     ...
; #pragma unroll
;   for (int r = 0; r < 16; ++r) p0[r] = __builtin_amdgcn_exp2f(p0[r]);
; template <int D0> __device__ __forceinline__ void pv_one(f32x16& od, int vb, bf16x8 pa0, bf16x8 pa1, bf16x8 pa2, bf16x8 pa3) {
;   const s16x4 l0 = tr_read<v_rd_off(D0, 0, 0)>(vb), h0 = tr_read<v_rd_off(D0, 0, 1)>(vb), l1 = tr_read<v_rd_off(D0, 1, 0)>(vb), h1 = tr_read<v_rd_off(D0, 1, 1)>(vb);
;   const s16x4 l2 = tr_read<v_rd_off(D0, 2, 0)>(vb), h2 = tr_read<v_rd_off(D0, 2, 1)>(vb), l3 = tr_read<v_rd_off(D0, 3, 0)>(vb), h3 = tr_read<v_rd_off(D0, 3, 1)>(vb);
;   asm volatile("s_waitcnt lgkmcnt(0)" ::: "memory"); SBAR();
;     ...
;   od = __builtin_amdgcn_mfma_f32_32x32x16_bf16(pa0, PK(l0, h0), od, 0, 0, 0);
;   od = __builtin_amdgcn_mfma_f32_32x32x16_bf16(pa1, PK(l1, h1), od, 0, 0, 0);
;   od = __builtin_amdgcn_mfma_f32_32x32x16_bf16(pa2, PK(l2, h2), od, 0, 0, 0);
;   od = __builtin_amdgcn_mfma_f32_32x32x16_bf16(pa3, PK(l3, h3), od, 0, 0, 0);
;     ...
; }
; __device__ __forceinline__ void pv_d0(f32x16* o, int vb, bf16x8 pa0, bf16x8 pa1, bf16x8 pa2, bf16x8 pa3) {
;   pv_one<0>(o[0], vb, pa0, pa1, pa2, pa3); pv_one<1>(o[1], vb, pa0, pa1, pa2, pa3); pv_one<2>(o[2], vb, pa0, pa1, pa2, pa3); pv_one<3>(o[3], vb, pa0, pa1, pa2, pa3);
.LBB0_330:
	v_exp_f32_e32 v112, v128
	v_exp_f32_e32 v113, v129
	v_exp_f32_e32 v114, v130
	v_exp_f32_e32 v115, v131
	v_exp_f32_e32 v116, v132
	v_exp_f32_e32 v117, v133
	v_exp_f32_e32 v118, v134
	v_exp_f32_e32 v119, v135
	v_exp_f32_e32 v120, v136
	v_exp_f32_e32 v121, v137
	v_exp_f32_e32 v122, v138
	v_exp_f32_e32 v123, v139
	v_exp_f32_e32 v124, v140
	v_exp_f32_e32 v125, v141
	v_exp_f32_e32 v126, v142
	v_exp_f32_e32 v127, v143
	s_lshl_b32 s0, s65, 14
	v_add_u32_e32 v128, s0, v219
	ds_read_b64_tr_b16 v[96:97], v128 offset:0
	ds_read_b64_tr_b16 v[98:99], v128 offset:0x800
	ds_read_b64_tr_b16 v[100:101], v128 offset:0x1000
	ds_read_b64_tr_b16 v[102:103], v128 offset:0x1800
	ds_read_b64_tr_b16 v[104:105], v128 offset:0x2000
	ds_read_b64_tr_b16 v[106:107], v128 offset:0x2800
	ds_read_b64_tr_b16 v[108:109], v128 offset:0x3000
	ds_read_b64_tr_b16 v[110:111], v128 offset:0x3800
	s_waitcnt lgkmcnt(0)
	s_nop 0
	v_mfma_f32_32x32x16_bf16 v[0:15], v[180:183], v[96:99], v[0:15]
	ds_read_b64_tr_b16 v[96:97], v128 offset:0x200
	ds_read_b64_tr_b16 v[98:99], v128 offset:0xa00
	v_mfma_f32_32x32x16_bf16 v[0:15], v[184:187], v[100:103], v[0:15]
	ds_read_b64_tr_b16 v[100:101], v128 offset:0x1200
	ds_read_b64_tr_b16 v[102:103], v128 offset:0x1a00
	v_mfma_f32_32x32x16_bf16 v[0:15], v[188:191], v[104:107], v[0:15]
	ds_read_b64_tr_b16 v[104:105], v128 offset:0x2200
	ds_read_b64_tr_b16 v[106:107], v128 offset:0x2a00
	v_mfma_f32_32x32x16_bf16 v[0:15], v[192:195], v[108:111], v[0:15]
	ds_read_b64_tr_b16 v[108:109], v128 offset:0x3200
	ds_read_b64_tr_b16 v[110:111], v128 offset:0x3a00
	s_waitcnt lgkmcnt(0)
	v_mfma_f32_32x32x16_bf16 v[16:31], v[180:183], v[96:99], v[16:31]
	ds_read_b64_tr_b16 v[96:97], v128 offset:0x400
	ds_read_b64_tr_b16 v[98:99], v128 offset:0xc00
	v_mfma_f32_32x32x16_bf16 v[16:31], v[184:187], v[100:103], v[16:31]
	ds_read_b64_tr_b16 v[100:101], v128 offset:0x1400
	ds_read_b64_tr_b16 v[102:103], v128 offset:0x1c00
	v_mfma_f32_32x32x16_bf16 v[16:31], v[188:191], v[104:107], v[16:31]
	ds_read_b64_tr_b16 v[104:105], v128 offset:0x2400
	ds_read_b64_tr_b16 v[106:107], v128 offset:0x2c00
	v_mfma_f32_32x32x16_bf16 v[16:31], v[192:195], v[108:111], v[16:31]
	ds_read_b64_tr_b16 v[108:109], v128 offset:0x3400
	ds_read_b64_tr_b16 v[110:111], v128 offset:0x3c00
	s_waitcnt lgkmcnt(0)
	v_mfma_f32_32x32x16_bf16 v[32:47], v[180:183], v[96:99], v[32:47]
	ds_read_b64_tr_b16 v[96:97], v128 offset:0x600
	ds_read_b64_tr_b16 v[98:99], v128 offset:0xe00
	v_mfma_f32_32x32x16_bf16 v[32:47], v[184:187], v[100:103], v[32:47]
	ds_read_b64_tr_b16 v[100:101], v128 offset:0x1600
	ds_read_b64_tr_b16 v[102:103], v128 offset:0x1e00
	v_mfma_f32_32x32x16_bf16 v[32:47], v[188:191], v[104:107], v[32:47]
	ds_read_b64_tr_b16 v[104:105], v128 offset:0x2600
	ds_read_b64_tr_b16 v[106:107], v128 offset:0x2e00
	v_mfma_f32_32x32x16_bf16 v[32:47], v[192:195], v[108:111], v[32:47]
	ds_read_b64_tr_b16 v[108:109], v128 offset:0x3600
	ds_read_b64_tr_b16 v[110:111], v128 offset:0x3e00
	s_waitcnt lgkmcnt(0)
	v_mfma_f32_32x32x16_bf16 v[48:63], v[180:183], v[96:99], v[48:63]
	s_add_i32 s0, s0, 0
	v_add_u32_e32 v96, s0, v221
	s_barrier
; #define SBAR() __builtin_amdgcn_sched_barrier(0)
; __device__ __forceinline__ void finishSM(f32x16& p0, f32x16& p1, float alpha, float& l_reg, bf16x8& pa0, bf16x8& pa1, bf16x8& pa2, bf16x8& pa3) {
; #pragma unroll
;   for (int r = 0; r < 16; ++r) p1[r] = __builtin_amdgcn_exp2f(p1[r]);
;   float ps = 0;
; #pragma unroll
;   for (int r = 0; r < 16; ++r) ps += p0[r];
; #pragma unroll
;   for (int r = 0; r < 16; ++r) ps += p1[r];
;   { auto rr = __builtin_amdgcn_permlane32_swap(__float_as_uint(ps), __float_as_uint(ps), false, false);
;     ps = __uint_as_float(rr[0]) + __uint_as_float(rr[1]); }
;   l_reg = l_reg * alpha + ps;
;     ...
;   PK4(p0, 0, pa0); PK4(p0, 8, pa1); PK4(p1, 0, pa2); PK4(p1, 8, pa3);
;     ...
; }
; __device__ __forceinline__ void qkt(f32x16& p0, f32x16& p1, const char* Ks, const bf16x8* qr, int r32, int hi) {
;   bf16x8 ka[4], kb[4];
; #pragma unroll
;   for (int d0 = 0; d0 < 4; ++d0) { const int cb = (d0 * 16 + hi * 8) * 2;
;     ka[d0] = *reinterpret_cast<const bf16x8*>(Ks + KSWZ64(r32, cb)); kb[d0] = *reinterpret_cast<const bf16x8*>(Ks + KSWZ64(32 + r32, cb)); }
;   asm volatile("s_waitcnt lgkmcnt(0)" ::: "memory"); SBAR();
;   p0 = f32x16{}; p1 = f32x16{};
; #pragma unroll
;   for (int d0 = 0; d0 < 4; ++d0) {
;     p0 = __builtin_amdgcn_mfma_f32_32x32x16_bf16(ka[d0], qr[d0], p0, 0, 0, 0);
;     p1 = __builtin_amdgcn_mfma_f32_32x32x16_bf16(kb[d0], qr[d0], p1, 0, 0, 0); }
; }
	s_waitcnt vmcnt(2)
	ds_write_b128 v96, v[168:171]
	v_add_u32_e32 v96, s0, v222
	v_mfma_f32_32x32x16_bf16 v[48:63], v[184:187], v[100:103], v[48:63]
	s_waitcnt vmcnt(1)
	ds_write_b128 v96, v[172:175]
	v_lshl_add_u32 v96, s65, 13, v224
	s_waitcnt vmcnt(0)
	ds_write_b128 v96, v[176:179] offset:49152
	v_mfma_f32_32x32x16_bf16 v[48:63], v[188:191], v[104:107], v[48:63]
	v_mfma_f32_32x32x16_bf16 v[48:63], v[192:195], v[108:111], v[48:63]
	v_add_f32_e32 v96, 0, v112
	v_add_f32_e32 v96, v113, v96
	v_add_f32_e32 v96, v114, v96
	v_add_f32_e32 v96, v115, v96
	v_add_f32_e32 v96, v116, v96
	v_add_f32_e32 v96, v117, v96
	v_add_f32_e32 v96, v118, v96
	v_add_f32_e32 v96, v119, v96
	v_add_f32_e32 v96, v120, v96
	v_add_f32_e32 v96, v121, v96
	v_add_f32_e32 v96, v122, v96
	v_add_f32_e32 v96, v123, v96
	v_exp_f32_e32 v80, v80
	v_add_f32_e32 v96, v124, v96
	v_exp_f32_e32 v81, v81
	v_add_f32_e32 v96, v125, v96
	v_exp_f32_e32 v82, v82
	v_add_f32_e32 v96, v126, v96
	v_exp_f32_e32 v83, v83
	v_add_f32_e32 v96, v127, v96
	v_exp_f32_e32 v84, v84
	v_add_f32_e32 v96, v80, v96
	v_exp_f32_e32 v85, v85
	v_add_f32_e32 v96, v81, v96
	v_exp_f32_e32 v86, v86
	v_add_f32_e32 v96, v82, v96
	v_exp_f32_e32 v87, v87
	v_add_f32_e32 v96, v83, v96
	v_exp_f32_e32 v88, v88
	v_add_f32_e32 v96, v84, v96
	v_exp_f32_e32 v89, v89
	v_add_f32_e32 v96, v85, v96
	v_exp_f32_e32 v90, v90
	v_add_f32_e32 v96, v86, v96
	v_exp_f32_e32 v91, v91
	v_add_f32_e32 v96, v87, v96
	v_exp_f32_e32 v92, v92
	v_add_f32_e32 v96, v88, v96
	v_exp_f32_e32 v93, v93
	v_add_f32_e32 v96, v89, v96
	v_exp_f32_e32 v94, v94
	v_add_f32_e32 v96, v90, v96
	v_exp_f32_e32 v95, v95
	v_add_f32_e32 v96, v91, v96
	v_add_f32_e32 v96, v92, v96
	v_add_f32_e32 v96, v93, v96
	v_add_f32_e32 v96, v94, v96
	v_add_f32_e32 v245, v95, v96
	v_mov_b32_e32 v246, v245
	v_cvt_pk_bf16_f32 v180, v112, v113
	v_cvt_pk_bf16_f32 v181, v114, v115
	v_cvt_pk_bf16_f32 v182, v116, v117
	v_cvt_pk_bf16_f32 v183, v118, v119
	v_cvt_pk_bf16_f32 v188, v120, v121
	v_cvt_pk_bf16_f32 v189, v122, v123
	v_cvt_pk_bf16_f32 v190, v124, v125
	v_cvt_pk_bf16_f32 v191, v126, v127
	v_cvt_pk_bf16_f32 v192, v80, v81
	v_cvt_pk_bf16_f32 v193, v82, v83
	v_cvt_pk_bf16_f32 v194, v84, v85
	v_cvt_pk_bf16_f32 v195, v86, v87
	v_cvt_pk_bf16_f32 v184, v88, v89
	v_cvt_pk_bf16_f32 v185, v90, v91
	v_cvt_pk_bf16_f32 v186, v92, v93
	v_cvt_pk_bf16_f32 v187, v94, v95
	s_nop 1
	v_permlane32_swap_b32_e32 v245, v246
	v_permlane32_swap_b32_e32 v180, v182
	v_permlane32_swap_b32_e32 v181, v183
	v_permlane32_swap_b32_e32 v188, v190
	v_permlane32_swap_b32_e32 v189, v191
	v_permlane32_swap_b32_e32 v192, v194
	v_permlane32_swap_b32_e32 v193, v195
	v_permlane32_swap_b32_e32 v184, v186
	v_permlane32_swap_b32_e32 v185, v187
	s_lshl_b32 s0, s67, 13
	s_add_i32 s0, s0, 0
	v_add_u32_e32 v84, s0, v226
	v_add_u32_e32 v92, s0, v229
	v_add_u32_e32 v100, s0, v231
	v_add_u32_e32 v108, s0, v240
	ds_read_b128 v[80:83], v84 offset:49152
	ds_read_b128 v[84:87], v84 offset:53248
	ds_read_b128 v[88:91], v92 offset:49152
	ds_read_b128 v[92:95], v92 offset:53248
	ds_read_b128 v[96:99], v100 offset:49152
	ds_read_b128 v[100:103], v100 offset:53248
	ds_read_b128 v[104:107], v108 offset:49152
	ds_read_b128 v[108:111], v108 offset:53248
	s_waitcnt lgkmcnt(0)
	s_waitcnt lgkmcnt(7)
	v_mfma_f32_32x32x16_bf16 v[128:143], v[80:83], v[164:167], 0
	s_waitcnt lgkmcnt(6)
	v_mfma_f32_32x32x16_bf16 v[112:127], v[84:87], v[164:167], 0
	s_waitcnt lgkmcnt(5)
	v_mfma_f32_32x32x16_bf16 v[128:143], v[88:91], v[160:163], v[128:143]
	s_waitcnt lgkmcnt(4)
	v_mfma_f32_32x32x16_bf16 v[112:127], v[92:95], v[160:163], v[112:127]
	s_waitcnt lgkmcnt(3)
	v_mfma_f32_32x32x16_bf16 v[128:143], v[96:99], v[152:155], v[128:143]
	s_waitcnt lgkmcnt(2)
	v_mfma_f32_32x32x16_bf16 v[112:127], v[100:103], v[152:155], v[112:127]
	s_waitcnt lgkmcnt(1)
	v_mfma_f32_32x32x16_bf16 v[128:143], v[104:107], v[156:159], v[128:143]
	s_waitcnt lgkmcnt(0)
	v_mfma_f32_32x32x16_bf16 v[112:127], v[108:111], v[156:159], v[112:127]
	s_cmp_lt_u32 s60, 61
	s_cselect_b64 s[0:1], -1, 0
	s_cmp_gt_u32 s60, 60
	s_cbranch_scc1 .LBB0_332
	s_add_u32 s74, s70, 0x18e00000
	s_addc_u32 s75, s71, 0
	global_load_dwordx4 v[168:171], v202, s[74:75] offset:2048
	s_add_u32 s74, s70, 0x18e40000
	s_addc_u32 s75, s71, 0
	global_load_dwordx4 v[172:175], v202, s[74:75] offset:2048
	s_add_u32 s74, s72, 0x18e00000
	s_addc_u32 s75, s73, 0
	global_load_dwordx4 v[176:179], v204, s[74:75] offset:1152

; #define SBAR() __builtin_amdgcn_sched_barrier(0)
; #define SLOAD(i, k0) do { sr_[i].vs0 = *(const GAS bf16x8*)(&Vh[(long)((k0) + sr) * LDK + sc]); sr_[i].vs1 = *(const GAS bf16x8*)(&Vh[(long)((k0) + 32 + sr) * LDK + sc]); \
;     sr_[i].ks0 = *(const GAS bf16x8*)(&Kh[(long)((k0) + kr) * LDK + kc]); } while (0)
; #define SWRITE(b, i) do { *(bf16x8*)(V_lds + (b) * SHM_V + vst0) = sr_[i].vs0; *(bf16x8*)(V_lds + (b) * SHM_V + vst1) = sr_[i].vs1; \
;     *(bf16x8*)(K_lds + (b) * SHM_K + kst) = sr_[i].ks0; } while (0)
; template <int D0> __device__ __forceinline__ void pv_one(f32x16& od, int vb, bf16x8 pa0, bf16x8 pa1, bf16x8 pa2, bf16x8 pa3) {
;   const s16x4 l0 = tr_read<v_rd_off(D0, 0, 0)>(vb), h0 = tr_read<v_rd_off(D0, 0, 1)>(vb), l1 = tr_read<v_rd_off(D0, 1, 0)>(vb), h1 = tr_read<v_rd_off(D0, 1, 1)>(vb);
;   const s16x4 l2 = tr_read<v_rd_off(D0, 2, 0)>(vb), h2 = tr_read<v_rd_off(D0, 2, 1)>(vb), l3 = tr_read<v_rd_off(D0, 3, 0)>(vb), h3 = tr_read<v_rd_off(D0, 3, 1)>(vb);
;   asm volatile("s_waitcnt lgkmcnt(0)" ::: "memory"); SBAR();
;     ...
;   od = __builtin_amdgcn_mfma_f32_32x32x16_bf16(pa0, PK(l0, h0), od, 0, 0, 0);
;   od = __builtin_amdgcn_mfma_f32_32x32x16_bf16(pa1, PK(l1, h1), od, 0, 0, 0);
;   od = __builtin_amdgcn_mfma_f32_32x32x16_bf16(pa2, PK(l2, h2), od, 0, 0, 0);
;   od = __builtin_amdgcn_mfma_f32_32x32x16_bf16(pa3, PK(l3, h3), od, 0, 0, 0);
;     ...
; }
; __device__ __forceinline__ void pv_d0(f32x16* o, int vb, bf16x8 pa0, bf16x8 pa1, bf16x8 pa2, bf16x8 pa3) {
;   pv_one<0>(o[0], vb, pa0, pa1, pa2, pa3); pv_one<1>(o[1], vb, pa0, pa1, pa2, pa3); pv_one<2>(o[2], vb, pa0, pa1, pa2, pa3); pv_one<3>(o[3], vb, pa0, pa1, pa2, pa3);
; template <bool GRPB> __device__ __forceinline__ void attn_pass(const float mbK, const float bmax2, const int pass, float* __restrict__ scr, bf16* __restrict__ mixrow, const float lam, const float* __restrict__ gsub, const float one_m_li, ...
;     ...
;   for (int t = 1; t + 1 < NT; t += 2) {
;     HSTEP(pB0, pB1, mnB, alB, pA0, pA1, alA, t * KVBLK, SLOAD(0, (t + 2) * KVBLK));
;     __syncthreads(); SWRITE(bm1, 0);
;     RESC(alB);
;     { const int tmp = bm1; bm1 = b0; b0 = bp1; bp1 = tmp; }
;     HSTEP(pA0, pA1, mnA, alA, pB0, pB1, alB, (t + 1) * KVBLK, if (t + 3 < NT) SLOAD(0, (t + 3) * KVBLK));
;     __syncthreads(); if (t + 3 < NT) SWRITE(bm1, 0);
;     RESC(alA);
;     { const int tmp = bm1; bm1 = b0; b0 = bp1; bp1 = tmp; }
.LBB0_336:
	s_lshl_b32 s8, s68, 14
	v_add_u32_e32 v128, s8, v219
	ds_read_b64_tr_b16 v[112:113], v128 offset:0
	ds_read_b64_tr_b16 v[114:115], v128 offset:0x800
	ds_read_b64_tr_b16 v[116:117], v128 offset:0x1000
	ds_read_b64_tr_b16 v[118:119], v128 offset:0x1800
	ds_read_b64_tr_b16 v[120:121], v128 offset:0x2000
	ds_read_b64_tr_b16 v[122:123], v128 offset:0x2800
	ds_read_b64_tr_b16 v[124:125], v128 offset:0x3000
	ds_read_b64_tr_b16 v[126:127], v128 offset:0x3800
	s_waitcnt lgkmcnt(0)
	s_nop 0
	v_mfma_f32_32x32x16_bf16 v[0:15], v[180:183], v[112:115], v[0:15]
	ds_read_b64_tr_b16 v[112:113], v128 offset:0x200
	ds_read_b64_tr_b16 v[114:115], v128 offset:0xa00
	v_mfma_f32_32x32x16_bf16 v[0:15], v[188:191], v[116:119], v[0:15]
	ds_read_b64_tr_b16 v[116:117], v128 offset:0x1200
	ds_read_b64_tr_b16 v[118:119], v128 offset:0x1a00
	v_mfma_f32_32x32x16_bf16 v[0:15], v[192:195], v[120:123], v[0:15]
	ds_read_b64_tr_b16 v[120:121], v128 offset:0x2200
	ds_read_b64_tr_b16 v[122:123], v128 offset:0x2a00
	v_mfma_f32_32x32x16_bf16 v[0:15], v[184:187], v[124:127], v[0:15]
	ds_read_b64_tr_b16 v[124:125], v128 offset:0x3200
	ds_read_b64_tr_b16 v[126:127], v128 offset:0x3a00
	s_waitcnt lgkmcnt(0)
	v_mfma_f32_32x32x16_bf16 v[16:31], v[180:183], v[112:115], v[16:31]
	ds_read_b64_tr_b16 v[112:113], v128 offset:0x400
	ds_read_b64_tr_b16 v[114:115], v128 offset:0xc00
	v_mfma_f32_32x32x16_bf16 v[16:31], v[188:191], v[116:119], v[16:31]
	ds_read_b64_tr_b16 v[116:117], v128 offset:0x1400
	ds_read_b64_tr_b16 v[118:119], v128 offset:0x1c00
	v_mfma_f32_32x32x16_bf16 v[16:31], v[192:195], v[120:123], v[16:31]
	ds_read_b64_tr_b16 v[120:121], v128 offset:0x2400
	ds_read_b64_tr_b16 v[122:123], v128 offset:0x2c00
	v_mfma_f32_32x32x16_bf16 v[16:31], v[184:187], v[124:127], v[16:31]
	ds_read_b64_tr_b16 v[124:125], v128 offset:0x3400
	ds_read_b64_tr_b16 v[126:127], v128 offset:0x3c00
	s_waitcnt lgkmcnt(0)
	v_mfma_f32_32x32x16_bf16 v[32:47], v[180:183], v[112:115], v[32:47]
	ds_read_b64_tr_b16 v[112:113], v128 offset:0x600
	ds_read_b64_tr_b16 v[114:115], v128 offset:0xe00
	v_mfma_f32_32x32x16_bf16 v[32:47], v[188:191], v[116:119], v[32:47]
	ds_read_b64_tr_b16 v[116:117], v128 offset:0x1600
	ds_read_b64_tr_b16 v[118:119], v128 offset:0x1e00
	v_mfma_f32_32x32x16_bf16 v[32:47], v[192:195], v[120:123], v[32:47]
	ds_read_b64_tr_b16 v[120:121], v128 offset:0x2600
	ds_read_b64_tr_b16 v[122:123], v128 offset:0x2e00
	v_mfma_f32_32x32x16_bf16 v[32:47], v[184:187], v[124:127], v[32:47]
	ds_read_b64_tr_b16 v[124:125], v128 offset:0x3600
	ds_read_b64_tr_b16 v[126:127], v128 offset:0x3e00
	s_waitcnt lgkmcnt(0)
	v_mfma_f32_32x32x16_bf16 v[48:63], v[180:183], v[112:115], v[48:63]
	s_mov_b64 s[54:55], -1
	s_andn2_b64 vcc, exec, s[0:1]
	s_barrier
	v_mfma_f32_32x32x16_bf16 v[48:63], v[188:191], v[116:119], v[48:63]
	v_mfma_f32_32x32x16_bf16 v[48:63], v[192:195], v[120:123], v[48:63]
	v_mfma_f32_32x32x16_bf16 v[48:63], v[184:187], v[124:127], v[48:63]
	s_cbranch_vccnz .LBB0_338
	s_add_i32 s0, s8, 0
	v_add_u32_e32 v114, s0, v221
	s_add_u32 s70, s70, s16
	s_addc_u32 s71, s71, s17
	s_add_u32 s72, s72, s16
	s_addc_u32 s73, s73, s17
	s_addk_i32 s66, 0x80
	v_add_u32_e32 v242, 0x200, v242
	s_add_i32 s60, s60, 2
	s_mov_b64 s[54:55], 0
	v_add_u32_e32 v112, s4, v223
	v_add_u32_e32 v113, s0, v222
	s_waitcnt vmcnt(2)
	ds_write_b128 v114, v[168:171]
	s_waitcnt vmcnt(1)
	ds_write_b128 v113, v[172:175]
	s_waitcnt vmcnt(0)
	ds_write_b128 v112, v[176:179] offset:49152

; __device__ __forceinline__ int v_rd_base(int lane) { return ((lane & 3) << 3) | (((lane >> 2) & 3) << 6) | (((lane >> 4) & 1) << 5) | (((lane >> 5) & 1) << 8); }
; #define SLOAD(i, k0) do { sr_[i].vs0 = *(const GAS bf16x8*)(&Vh[(long)((k0) + sr) * LDK + sc]); sr_[i].vs1 = *(const GAS bf16x8*)(&Vh[(long)((k0) + 32 + sr) * LDK + sc]); \
;     sr_[i].ks0 = *(const GAS bf16x8*)(&Kh[(long)((k0) + kr) * LDK + kc]); } while (0)
; __device__ __forceinline__ void finishSM(f32x16& p0, f32x16& p1, float alpha, float& l_reg, bf16x8& pa0, bf16x8& pa1, bf16x8& pa2, bf16x8& pa3) {
; #pragma unroll
;   for (int r = 0; r < 16; ++r) p1[r] = __builtin_amdgcn_exp2f(p1[r]);
;   float ps = 0;
; #pragma unroll
;   for (int r = 0; r < 16; ++r) ps += p0[r];
; #pragma unroll
;   for (int r = 0; r < 16; ++r) ps += p1[r];
;   { auto rr = __builtin_amdgcn_permlane32_swap(__float_as_uint(ps), __float_as_uint(ps), false, false);
;     ps = __uint_as_float(rr[0]) + __uint_as_float(rr[1]); }
;   l_reg = l_reg * alpha + ps;
;     ...
;   PK4(p0, 0, pa0); PK4(p0, 8, pa1); PK4(p1, 0, pa2); PK4(p1, 8, pa3);
;     ...
; }
; __device__ __forceinline__ void qkt(f32x16& p0, f32x16& p1, const char* Ks, const bf16x8* qr, int r32, int hi) {
;   bf16x8 ka[4], kb[4];
; #pragma unroll
;   for (int d0 = 0; d0 < 4; ++d0) { const int cb = (d0 * 16 + hi * 8) * 2;
;     ka[d0] = *reinterpret_cast<const bf16x8*>(Ks + KSWZ64(r32, cb)); kb[d0] = *reinterpret_cast<const bf16x8*>(Ks + KSWZ64(32 + r32, cb)); }
; template <bool GRPB> __device__ __forceinline__ void attn_pass(const float mbK, const float bmax2, const int pass, float* __restrict__ scr, bf16* __restrict__ mixrow, const float lam, const float* __restrict__ gsub, const float one_m_li, ...
;     ...
;   const int vb0 = (int)(uintptr_t)V_lds + v_rd_base(lane);
;   struct { bf16x8 vs0, vs1, ks0; } sr_[2];
;     ...
;   f32x16 pA0, pA1, pB0, pB1; float mnA, mnB, alA, alB; bf16x8 pa0, pa1, pa2, pa3; constexpr int NT = SEQ / KVBLK;
;   __syncthreads();
;   SLOAD(0, 0); SLOAD(1, KVBLK); asm volatile("s_waitcnt vmcnt(0)" ::: "memory"); SWRITE(0, 0); SWRITE(1, 1);
;   SLOAD(0, 2 * KVBLK); asm volatile("s_waitcnt vmcnt(0)" ::: "memory"); SWRITE(2, 0); __syncthreads();
;   qkt(pA0, pA1, K_lds, qr, r32, hi); partialSM(pA0, pA1, m_reg, mnA, alA, 0, qpos, qw, hi, tb2, cL, cR);
;   int bm1 = 0, b0 = 1, bp1 = 2;
;     ...
;   for (int t = 1; t + 1 < NT; t += 2) {
.LBB0_352:
	v_and_b32_e32 v193, 63, v146
	s_nop 7
	v_lshlrev_b32_e32 v2, 4, v193
	v_lshlrev_b32_e32 v1, 3, v193
	v_and_b32_e32 v2, 0xc0, v2
	v_lshlrev_b32_e32 v3, 1, v193
	v_and_or_b32 v2, v1, 24, v2
	v_and_b32_e32 v3, 32, v3
	v_and_b32_e32 v1, 0x100, v1
	v_and_b32_e32 v4, 15, v146
	v_or3_b32 v209, v2, v3, v1
	v_lshl_add_u64 v[2:3], s[48:49], 0, v[50:51]
	v_lshlrev_b32_e32 v4, 4, v4
	v_mov_b32_e32 v5, v144
	v_lshl_add_u64 v[2:3], v[2:3], 0, v[4:5]
	v_and_b32_e32 v4, 7, v146
	s_cmp_lg_u32 0, -1
	v_exp_f32_e32 v173, v34
	v_exp_f32_e32 v175, v35
	v_exp_f32_e32 v171, v36
	v_exp_f32_e32 v174, v37
	v_exp_f32_e32 v169, v38
	v_exp_f32_e32 v172, v39
	v_exp_f32_e32 v168, v40
	v_exp_f32_e32 v170, v41
	v_exp_f32_e32 v133, v42
	v_exp_f32_e32 v135, v43
	v_exp_f32_e32 v131, v44
	v_exp_f32_e32 v134, v45
	v_exp_f32_e32 v129, v46
	v_exp_f32_e32 v132, v47
	v_exp_f32_e32 v128, v48
	v_exp_f32_e32 v130, v49
	v_lshl_add_u64 v[182:183], s[18:19], 0, v[2:3]
	v_lshl_add_u64 v[2:3], s[48:49], 0, v[52:53]
	v_lshlrev_b32_e32 v4, 4, v4
	s_cselect_b32 s1, 0, 0
	v_lshl_add_u64 v[2:3], v[2:3], 0, v[4:5]
	v_add_u32_e32 v194, s1, v209
	s_lshl_b32 s1, s59, 4
	v_lshl_add_u64 v[184:185], s[18:19], 0, v[2:3]
	v_sub_u32_e32 v2, v180, v54
	s_add_i32 s59, 0, 0x12c00
	v_mov_b32_e32 v195, 0
	s_mov_b32 s61, 1
	s_mov_b32 s0, 0
	v_mov_b32_e32 v1, v0
	v_mov_b32_e32 v66, v0
	v_mov_b32_e32 v67, v0
	v_mov_b32_e32 v68, v0
	v_mov_b32_e32 v69, v0
	v_mov_b32_e32 v70, v0
	v_mov_b32_e32 v71, v0
	v_mov_b32_e32 v72, v0
	s_and_b32 s2, s1, 0x300
	s_sub_i32 s62, 0x7f, s60
	s_mov_b32 s63, 2
	v_add_u32_e32 v215, s59, v2
	s_mov_b32 s64, 1
	v_mov_b32_e32 v2, 0
	v_mov_b32_e32 v3, v195
	v_mov_b32_e32 v4, v195
	v_mov_b32_e32 v5, v195
	v_mov_b32_e32 v6, v195
	v_mov_b32_e32 v7, v195
	v_mov_b32_e32 v8, v195
	v_mov_b32_e32 v9, v195
	v_mov_b32_e32 v10, v195
	v_mov_b32_e32 v11, v195
	v_mov_b32_e32 v12, v195
	v_mov_b32_e32 v13, v195
	v_mov_b32_e32 v14, v195
	v_mov_b32_e32 v15, v195
	v_mov_b32_e32 v16, v195
	v_mov_b32_e32 v17, v195
	v_mov_b32_e32 v18, 0
	v_mov_b32_e32 v19, v195
	v_mov_b32_e32 v20, v195
	v_mov_b32_e32 v21, v195
	v_mov_b32_e32 v22, v195
	v_mov_b32_e32 v23, v195
	v_mov_b32_e32 v24, v195
	v_mov_b32_e32 v25, v195
	v_mov_b32_e32 v26, v195
	v_mov_b32_e32 v27, v195
	v_mov_b32_e32 v28, v195
	v_mov_b32_e32 v29, v195
	v_mov_b32_e32 v30, v195
	v_mov_b32_e32 v31, v195
	v_mov_b32_e32 v32, v195
	v_mov_b32_e32 v33, v195
	v_mov_b32_e32 v34, 0
	v_mov_b32_e32 v35, v195
	v_mov_b32_e32 v36, v195
	v_mov_b32_e32 v37, v195
	v_mov_b32_e32 v38, v195
	v_mov_b32_e32 v39, v195
	v_mov_b32_e32 v40, v195
	v_mov_b32_e32 v41, v195
	v_mov_b32_e32 v42, v195
	v_mov_b32_e32 v43, v195
	v_mov_b32_e32 v44, v195
	v_mov_b32_e32 v45, v195
	v_mov_b32_e32 v46, v195
	v_mov_b32_e32 v47, v195
	v_mov_b32_e32 v48, v195
	v_mov_b32_e32 v49, v195
	v_mov_b32_e32 v50, 0
	v_mov_b32_e32 v51, v195
	v_mov_b32_e32 v52, v195
	v_mov_b32_e32 v53, v195
	v_mov_b32_e32 v54, v195
	v_mov_b32_e32 v55, v195
	v_mov_b32_e32 v56, v195
	v_mov_b32_e32 v57, v195
	v_mov_b32_e32 v58, v195
	v_mov_b32_e32 v59, v195
	v_mov_b32_e32 v60, v195
	v_mov_b32_e32 v61, v195
	v_mov_b32_e32 v62, v195
	v_mov_b32_e32 v63, v195
	v_mov_b32_e32 v64, v195
	v_mov_b32_e32 v65, v195
	v_mov_b32_e32 v75, v0
	v_mov_b32_e32 v74, v0
	v_mov_b32_e32 v73, v0
	v_mov_b32_e32 v78, v0
	v_mov_b32_e32 v79, v0
	v_mov_b32_e32 v76, v0
	v_mov_b32_e32 v77, v0
	s_nop 0
	v_readfirstlane_b32 s70, v182
	v_readfirstlane_b32 s71, v183
	v_readfirstlane_b32 s72, v184
	v_readfirstlane_b32 s73, v185
	s_nop 1
	v_subrev_u32_e32 v182, s70, v182
	v_subrev_u32_e32 v184, s72, v184
	s_add_u32 s70, s70, s2
	s_addc_u32 s71, s71, s3
	s_add_u32 s72, s72, s2
	s_addc_u32 s73, s73, s3
.LBB0_353:
	s_mov_b32 s65, s61
	s_mov_b32 s61, s0
	s_lshl_b32 s0, s65, 13
	s_add_i32 s36, s0, 0
	v_add_u32_e32 v100, s36, v202
	v_add_u32_e32 v104, s36, v205
	ds_read_b128 v[96:99], v100 offset:49152
	ds_read_b128 v[100:103], v100 offset:53248
	ds_read_b128 v[136:139], v104 offset:49152
	ds_read_b128 v[140:143], v104 offset:53248
	v_add_u32_e32 v104, s36, v207
	s_waitcnt vmcnt(0)
	ds_read_b128 v[176:179], v104 offset:49152
	ds_read_b128 v[186:189], v104 offset:53248
	v_add_u32_e32 v104, s36, v208
	ds_read_b128 v[218:221], v104 offset:49152
	ds_read_b128 v[222:225], v104 offset:53248
	s_waitcnt lgkmcnt(0)
	v_exp_f32_e32 v226, v80
	v_add_f32_e32 v80, 0, v173
	v_add_f32_e32 v80, v175, v80
	s_waitcnt lgkmcnt(7)
	v_mfma_f32_32x32x16_bf16 v[112:127], v[96:99], v[164:167], 0
	v_add_f32_e32 v80, v171, v80
	v_add_f32_e32 v80, v174, v80
	v_add_f32_e32 v80, v169, v80
	v_add_f32_e32 v80, v172, v80
	v_add_f32_e32 v80, v168, v80
	v_add_f32_e32 v80, v170, v80
	v_add_f32_e32 v80, v133, v80
	s_waitcnt lgkmcnt(6)
	v_mfma_f32_32x32x16_bf16 v[96:111], v[100:103], v[164:167], 0
	v_add_f32_e32 v80, v135, v80
	v_add_f32_e32 v80, v131, v80
	v_add_f32_e32 v80, v134, v80
	v_add_f32_e32 v80, v129, v80
	v_exp_f32_e32 v227, v81
	v_add_f32_e32 v80, v132, v80
	v_exp_f32_e32 v228, v82
	s_waitcnt lgkmcnt(5)
	v_mfma_f32_32x32x16_bf16 v[112:127], v[136:139], v[160:163], v[112:127]
	v_add_f32_e32 v80, v128, v80
	v_exp_f32_e32 v229, v83
	v_add_f32_e32 v80, v130, v80
	v_exp_f32_e32 v230, v84
	v_add_f32_e32 v80, v226, v80
	v_exp_f32_e32 v231, v85
	v_add_f32_e32 v80, v227, v80
	s_waitcnt lgkmcnt(4)
	v_mfma_f32_32x32x16_bf16 v[96:111], v[140:143], v[160:163], v[96:111]
	v_exp_f32_e32 v240, v86
	v_add_f32_e32 v80, v228, v80
	v_exp_f32_e32 v241, v87
	v_add_f32_e32 v80, v229, v80
	v_exp_f32_e32 v242, v88
	v_add_f32_e32 v80, v230, v80
	v_exp_f32_e32 v243, v89
	s_waitcnt lgkmcnt(3)
; __device__ __forceinline__ void finishSM(f32x16& p0, f32x16& p1, float alpha, float& l_reg, bf16x8& pa0, bf16x8& pa1, bf16x8& pa2, bf16x8& pa3) {
; #pragma unroll
;   for (int r = 0; r < 16; ++r) p1[r] = __builtin_amdgcn_exp2f(p1[r]);
;   float ps = 0;
; #pragma unroll
;   for (int r = 0; r < 16; ++r) ps += p0[r];
; #pragma unroll
;   for (int r = 0; r < 16; ++r) ps += p1[r];
;   { auto rr = __builtin_amdgcn_permlane32_swap(__float_as_uint(ps), __float_as_uint(ps), false, false);
;     ps = __uint_as_float(rr[0]) + __uint_as_float(rr[1]); }
;   l_reg = l_reg * alpha + ps;
;     ...
;   PK4(p0, 0, pa0); PK4(p0, 8, pa1); PK4(p1, 0, pa2); PK4(p1, 8, pa3);
;     ...
; }
; __device__ __forceinline__ void qkt(f32x16& p0, f32x16& p1, const char* Ks, const bf16x8* qr, int r32, int hi) {
;   bf16x8 ka[4], kb[4];
; #pragma unroll
;   for (int d0 = 0; d0 < 4; ++d0) { const int cb = (d0 * 16 + hi * 8) * 2;
;     ka[d0] = *reinterpret_cast<const bf16x8*>(Ks + KSWZ64(r32, cb)); kb[d0] = *reinterpret_cast<const bf16x8*>(Ks + KSWZ64(32 + r32, cb)); }
;   asm volatile("s_waitcnt lgkmcnt(0)" ::: "memory"); SBAR();
;   p0 = f32x16{}; p1 = f32x16{};
; #pragma unroll
;   for (int d0 = 0; d0 < 4; ++d0) {
;     p0 = __builtin_amdgcn_mfma_f32_32x32x16_bf16(ka[d0], qr[d0], p0, 0, 0, 0);
;     p1 = __builtin_amdgcn_mfma_f32_32x32x16_bf16(kb[d0], qr[d0], p1, 0, 0, 0); }
; }
; __device__ __forceinline__ int v_st(int k, int c) { const int kk = (k & ~0xC) | ((k & 4) << 1) | ((k & 8) >> 1); return ((kk >> 3) * 4 + (c >> 5)) * 512 + ((kk & 7) * 32 + (c & 31)) * 2; }
; __device__ __forceinline__ int v_rd_base(int lane) { return ((lane & 3) << 3) | (((lane >> 2) & 3) << 6) | (((lane >> 4) & 1) << 5) | (((lane >> 5) & 1) << 8); }
; template <int OFF> __device__ __forceinline__ s16x4 tr_read(int vb) {
;   s16x4 r; asm volatile("ds_read_b64_tr_b16 %0, %1 offset:%2" : "=&v"(r) : "v"(vb), "i"(OFF) : "memory"); return r;
; }
; template <int D0> __device__ __forceinline__ void pv_one(f32x16& od, int vb, bf16x8 pa0, bf16x8 pa1, bf16x8 pa2, bf16x8 pa3) {
;   const s16x4 l0 = tr_read<v_rd_off(D0, 0, 0)>(vb), h0 = tr_read<v_rd_off(D0, 0, 1)>(vb), l1 = tr_read<v_rd_off(D0, 1, 0)>(vb), h1 = tr_read<v_rd_off(D0, 1, 1)>(vb);
;   const s16x4 l2 = tr_read<v_rd_off(D0, 2, 0)>(vb), h2 = tr_read<v_rd_off(D0, 2, 1)>(vb), l3 = tr_read<v_rd_off(D0, 3, 0)>(vb), h3 = tr_read<v_rd_off(D0, 3, 1)>(vb);
	v_mfma_f32_32x32x16_bf16 v[112:127], v[176:179], v[156:159], v[112:127]
	v_add_f32_e32 v80, v231, v80
	v_exp_f32_e32 v244, v90
	v_add_f32_e32 v80, v240, v80
	v_exp_f32_e32 v245, v91
	v_add_f32_e32 v80, v241, v80
	v_exp_f32_e32 v246, v92
	v_add_f32_e32 v80, v242, v80
	s_waitcnt lgkmcnt(2)
	v_mfma_f32_32x32x16_bf16 v[96:111], v[186:189], v[156:159], v[96:111]
	v_exp_f32_e32 v247, v93
	v_add_f32_e32 v80, v243, v80
	v_exp_f32_e32 v248, v94
	v_add_f32_e32 v80, v244, v80
	v_exp_f32_e32 v95, v95
	v_add_f32_e32 v80, v245, v80
	v_add_f32_e32 v80, v246, v80
	s_waitcnt lgkmcnt(1)
	v_mfma_f32_32x32x16_bf16 v[112:127], v[218:221], v[152:155], v[112:127]
	v_add_f32_e32 v80, v247, v80
	v_add_f32_e32 v80, v248, v80
	v_add_f32_e32 v216, v95, v80
	v_mov_b32_e32 v217, v216
	v_cvt_pk_bf16_f32 v80, v173, v175
	v_cvt_pk_bf16_f32 v81, v171, v174
	v_cvt_pk_bf16_f32 v82, v169, v172
	s_waitcnt lgkmcnt(0)
	v_mfma_f32_32x32x16_bf16 v[96:111], v[222:225], v[152:155], v[96:111]
	v_cvt_pk_bf16_f32 v83, v168, v170
	v_cvt_pk_bf16_f32 v84, v133, v135
	v_cvt_pk_bf16_f32 v85, v131, v134
	v_cvt_pk_bf16_f32 v86, v129, v132
	v_cvt_pk_bf16_f32 v87, v128, v130
	v_cvt_pk_bf16_f32 v88, v226, v227
	v_cvt_pk_bf16_f32 v89, v228, v229
	v_cvt_pk_bf16_f32 v90, v230, v231
	v_cvt_pk_bf16_f32 v91, v240, v241
	v_cvt_pk_bf16_f32 v92, v242, v243
	v_cvt_pk_bf16_f32 v93, v244, v245
	v_cvt_pk_bf16_f32 v94, v246, v247
	v_cvt_pk_bf16_f32 v95, v248, v95
	v_permlane32_swap_b32_e32 v216, v217
	v_permlane32_swap_b32_e32 v80, v82
	v_permlane32_swap_b32_e32 v81, v83
	v_permlane32_swap_b32_e32 v84, v86
	v_permlane32_swap_b32_e32 v85, v87
	v_permlane32_swap_b32_e32 v88, v90
	v_permlane32_swap_b32_e32 v89, v91
	v_permlane32_swap_b32_e32 v92, v94
	v_permlane32_swap_b32_e32 v93, v95
	s_mov_b32 s0, 0x18dc0000
	s_add_u32 s74, s70, s15
	s_addc_u32 s75, s71, 0
	global_load_dwordx4 v[168:171], v182, s[74:75] offset:2048
	s_add_u32 s74, s70, s0
	s_addc_u32 s75, s71, 0
	global_load_dwordx4 v[172:175], v182, s[74:75] offset:2048
	s_add_u32 s74, s72, s15
	s_addc_u32 s75, s73, 0
	global_load_dwordx4 v[176:179], v184, s[74:75] offset:1024
	s_lshl_b32 s4, s61, 14
	v_add_u32_e32 v218, s4, v194
	ds_read_b64_tr_b16 v[128:129], v218 offset:0
	ds_read_b64_tr_b16 v[130:131], v218 offset:0x800
	ds_read_b64_tr_b16 v[132:133], v218 offset:0x1000
	ds_read_b64_tr_b16 v[134:135], v218 offset:0x1800
	ds_read_b64_tr_b16 v[136:137], v218 offset:0x2000
	ds_read_b64_tr_b16 v[138:139], v218 offset:0x2800
	ds_read_b64_tr_b16 v[140:141], v218 offset:0x3000
	ds_read_b64_tr_b16 v[142:143], v218 offset:0x3800
	s_waitcnt lgkmcnt(0)
	s_nop 0
	v_mfma_f32_32x32x16_bf16 v[2:17], v[80:83], v[128:131], v[2:17]
	ds_read_b64_tr_b16 v[128:129], v218 offset:0x200
	ds_read_b64_tr_b16 v[130:131], v218 offset:0xa00
	v_mfma_f32_32x32x16_bf16 v[2:17], v[84:87], v[132:135], v[2:17]
	ds_read_b64_tr_b16 v[132:133], v218 offset:0x1200
	ds_read_b64_tr_b16 v[134:135], v218 offset:0x1a00
	v_mfma_f32_32x32x16_bf16 v[2:17], v[88:91], v[136:139], v[2:17]
	ds_read_b64_tr_b16 v[136:137], v218 offset:0x2200
	ds_read_b64_tr_b16 v[138:139], v218 offset:0x2a00
	v_mfma_f32_32x32x16_bf16 v[2:17], v[92:95], v[140:143], v[2:17]
	ds_read_b64_tr_b16 v[140:141], v218 offset:0x3200
	ds_read_b64_tr_b16 v[142:143], v218 offset:0x3a00
	s_waitcnt lgkmcnt(0)
	v_mfma_f32_32x32x16_bf16 v[18:33], v[80:83], v[128:131], v[18:33]
	ds_read_b64_tr_b16 v[128:129], v218 offset:0x400
	ds_read_b64_tr_b16 v[130:131], v218 offset:0xc00
	v_mfma_f32_32x32x16_bf16 v[18:33], v[84:87], v[132:135], v[18:33]
	ds_read_b64_tr_b16 v[132:133], v218 offset:0x1400
	ds_read_b64_tr_b16 v[134:135], v218 offset:0x1c00
	v_mfma_f32_32x32x16_bf16 v[18:33], v[88:91], v[136:139], v[18:33]
	ds_read_b64_tr_b16 v[136:137], v218 offset:0x2400
	ds_read_b64_tr_b16 v[138:139], v218 offset:0x2c00
	v_mfma_f32_32x32x16_bf16 v[18:33], v[92:95], v[140:143], v[18:33]
	ds_read_b64_tr_b16 v[140:141], v218 offset:0x3400
	ds_read_b64_tr_b16 v[142:143], v218 offset:0x3c00
	s_waitcnt lgkmcnt(0)
	v_mfma_f32_32x32x16_bf16 v[34:49], v[80:83], v[128:131], v[34:49]
	ds_read_b64_tr_b16 v[128:129], v218 offset:0x600
	ds_read_b64_tr_b16 v[130:131], v218 offset:0xe00
	v_mfma_f32_32x32x16_bf16 v[34:49], v[84:87], v[132:135], v[34:49]
	ds_read_b64_tr_b16 v[132:133], v218 offset:0x1600
	ds_read_b64_tr_b16 v[134:135], v218 offset:0x1e00
	v_mfma_f32_32x32x16_bf16 v[34:49], v[88:91], v[136:139], v[34:49]
	ds_read_b64_tr_b16 v[136:137], v218 offset:0x2600
	ds_read_b64_tr_b16 v[138:139], v218 offset:0x2e00
	v_mfma_f32_32x32x16_bf16 v[34:49], v[92:95], v[140:143], v[34:49]
	ds_read_b64_tr_b16 v[140:141], v218 offset:0x3600
	ds_read_b64_tr_b16 v[142:143], v218 offset:0x3e00
	s_waitcnt lgkmcnt(0)
	v_mfma_f32_32x32x16_bf16 v[50:65], v[80:83], v[128:131], v[50:65]
	s_add_i32 s5, s62, 0xffffff47
	s_mov_b64 s[0:1], -1
	s_cmp_gt_u32 s5, 0xfffffeec
	v_mfma_f32_32x32x16_bf16 v[50:65], v[84:87], v[132:135], v[50:65]
	v_mfma_f32_32x32x16_bf16 v[50:65], v[88:91], v[136:139], v[50:65]
	v_mfma_f32_32x32x16_bf16 v[50:65], v[92:95], v[140:143], v[50:65]
	s_cbranch_scc0 .LBB0_355
; __device__ __forceinline__ void partialSM(f32x16& p0, f32x16& p1, float& m_reg, float& mn, float& alpha, int kt0, int qpos, int qw, int hi, const float* tb2, float cL, float cR) {
;   mn = m_reg; alpha = 1.f;
;   const int rel_hi = kt0 + 63 - qw, rel_lo = kt0 - (qw + 31);
;   if (rel_hi <= -91 || rel_lo >= 91) {
;     const float cm = ((rel_hi <= -91) ? cL : cR) - m_reg;
; #pragma unroll
;     for (int r = 0; r < 16; ++r) { p0[r] = fmaf(p0[r], C1, cm); p1[r] = fmaf(p1[r], C1, cm); }
;   } else {
;     const float* tp = tb2 + (kt0 - qpos + 192 + 4 * hi);
; #pragma unroll
;     for (int r4 = 0; r4 < 4; ++r4) {
;       float ta[4], tb[4];
; #pragma unroll
;       for (int i = 0; i < 4; ++i) { ta[i] = tp[8 * r4 + i] - m_reg; tb[i] = tp[32 + 8 * r4 + i] - m_reg; }
; #pragma unroll
;       for (int i = 0; i < 4; ++i) { p0[4 * r4 + i] = fmaf(p0[4 * r4 + i], C1, ta[i]); p1[4 * r4 + i] = fmaf(p1[4 * r4 + i], C1, tb[i]); }
	ds_read2_b32 v[80:81], v215 offset1:1
	ds_read2_b32 v[128:129], v215 offset0:32 offset1:33
	ds_read2_b32 v[130:131], v215 offset0:34 offset1:35
	ds_read2_b32 v[82:83], v215 offset0:2 offset1:3
	ds_read2_b32 v[84:85], v215 offset0:8 offset1:9
	ds_read2_b32 v[132:133], v215 offset0:40 offset1:41
	ds_read2_b32 v[134:135], v215 offset0:42 offset1:43
	ds_read2_b32 v[86:87], v215 offset0:10 offset1:11
	ds_read2_b32 v[88:89], v215 offset0:16 offset1:17
	ds_read2_b32 v[136:137], v215 offset0:48 offset1:49
	ds_read2_b32 v[138:139], v215 offset0:50 offset1:51
	ds_read2_b32 v[90:91], v215 offset0:18 offset1:19
	ds_read2_b32 v[92:93], v215 offset0:24 offset1:25
	ds_read2_b32 v[94:95], v215 offset0:26 offset1:27
	ds_read2_b32 v[140:141], v215 offset0:56 offset1:57
	ds_read2_b32 v[142:143], v215 offset0:58 offset1:59
	s_waitcnt lgkmcnt(3)
	v_sub_f32_e32 v93, v93, v79
	v_sub_f32_e32 v92, v92, v78
	s_waitcnt lgkmcnt(2)
	v_sub_f32_e32 v95, v95, v77
	v_sub_f32_e32 v94, v94, v76
	v_sub_f32_e32 v89, v89, v75
	v_sub_f32_e32 v88, v88, v72
	v_sub_f32_e32 v91, v91, v73
	v_sub_f32_e32 v90, v90, v74
	v_sub_f32_e32 v85, v85, v69
	v_sub_f32_e32 v84, v84, v68
	v_sub_f32_e32 v87, v87, v71
	v_sub_f32_e32 v86, v86, v70
	v_sub_f32_e32 v81, v81, v1
	v_sub_f32_e32 v80, v80, v0
	v_sub_f32_e32 v83, v83, v67
	v_sub_f32_e32 v82, v82, v66
	s_waitcnt lgkmcnt(1)
	v_sub_f32_e32 v141, v141, v79
	v_sub_f32_e32 v140, v140, v78
	s_waitcnt lgkmcnt(0)
	v_sub_f32_e32 v143, v143, v77
	v_sub_f32_e32 v142, v142, v76
	v_sub_f32_e32 v137, v137, v75
	v_sub_f32_e32 v136, v136, v72
	v_sub_f32_e32 v139, v139, v73
	v_sub_f32_e32 v138, v138, v74
	v_sub_f32_e32 v133, v133, v69
	v_sub_f32_e32 v132, v132, v68
	v_sub_f32_e32 v135, v135, v71
	v_sub_f32_e32 v134, v134, v70
	v_sub_f32_e32 v129, v129, v1
	v_sub_f32_e32 v128, v128, v0
	v_sub_f32_e32 v131, v131, v67
	v_sub_f32_e32 v130, v130, v66
	v_pk_fma_f32 v[82:83], v[114:115], s[6:7], v[82:83] op_sel_hi:[1,0,1]
	v_pk_fma_f32 v[80:81], v[112:113], s[6:7], v[80:81] op_sel_hi:[1,0,1]
	v_pk_fma_f32 v[86:87], v[118:119], s[6:7], v[86:87] op_sel_hi:[1,0,1]
	v_pk_fma_f32 v[84:85], v[116:117], s[6:7], v[84:85] op_sel_hi:[1,0,1]
	v_pk_fma_f32 v[90:91], v[122:123], s[6:7], v[90:91] op_sel_hi:[1,0,1]
	v_pk_fma_f32 v[88:89], v[120:121], s[6:7], v[88:89] op_sel_hi:[1,0,1]
	v_pk_fma_f32 v[94:95], v[126:127], s[6:7], v[94:95] op_sel_hi:[1,0,1]
	v_pk_fma_f32 v[92:93], v[124:125], s[6:7], v[92:93] op_sel_hi:[1,0,1]
	v_pk_fma_f32 v[130:131], v[98:99], s[6:7], v[130:131] op_sel_hi:[1,0,1]
	v_pk_fma_f32 v[128:129], v[96:97], s[6:7], v[128:129] op_sel_hi:[1,0,1]
	v_pk_fma_f32 v[134:135], v[102:103], s[6:7], v[134:135] op_sel_hi:[1,0,1]
	v_pk_fma_f32 v[132:133], v[100:101], s[6:7], v[132:133] op_sel_hi:[1,0,1]
	v_pk_fma_f32 v[138:139], v[106:107], s[6:7], v[138:139] op_sel_hi:[1,0,1]
	v_pk_fma_f32 v[136:137], v[104:105], s[6:7], v[136:137] op_sel_hi:[1,0,1]
	v_pk_fma_f32 v[142:143], v[110:111], s[6:7], v[142:143] op_sel_hi:[1,0,1]
	v_pk_fma_f32 v[140:141], v[108:109], s[6:7], v[140:141] op_sel_hi:[1,0,1]
	s_mov_b64 s[0:1], 0

; #define SBAR() __builtin_amdgcn_sched_barrier(0)
; #define SLOAD(i, k0) do { sr_[i].vs0 = *(const GAS bf16x8*)(&Vh[(long)((k0) + sr) * LDK + sc]); sr_[i].vs1 = *(const GAS bf16x8*)(&Vh[(long)((k0) + 32 + sr) * LDK + sc]); \
;     sr_[i].ks0 = *(const GAS bf16x8*)(&Kh[(long)((k0) + kr) * LDK + kc]); } while (0)
; __device__ __forceinline__ void partialSM(f32x16& p0, f32x16& p1, float& m_reg, float& mn, float& alpha, int kt0, int qpos, int qw, int hi, const float* tb2, float cL, float cR) {
;     ...
;   for (int r = 0; r < 16; ++r) p0[r] = __builtin_amdgcn_exp2f(p0[r]);
; }
; __device__ __forceinline__ void finishSM(f32x16& p0, f32x16& p1, float alpha, float& l_reg, bf16x8& pa0, bf16x8& pa1, bf16x8& pa2, bf16x8& pa3) {
; #pragma unroll
;   for (int r = 0; r < 16; ++r) p1[r] = __builtin_amdgcn_exp2f(p1[r]);
;   float ps = 0;
; #pragma unroll
;   for (int r = 0; r < 16; ++r) ps += p0[r];
; #pragma unroll
;   for (int r = 0; r < 16; ++r) ps += p1[r];
;   { auto rr = __builtin_amdgcn_permlane32_swap(__float_as_uint(ps), __float_as_uint(ps), false, false);
;     ps = __uint_as_float(rr[0]) + __uint_as_float(rr[1]); }
;   l_reg = l_reg * alpha + ps;
;     ...
;   PK4(p0, 0, pa0); PK4(p0, 8, pa1); PK4(p1, 0, pa2); PK4(p1, 8, pa3);
;     ...
; }
; __device__ __forceinline__ void qkt(f32x16& p0, f32x16& p1, const char* Ks, const bf16x8* qr, int r32, int hi) {
;   bf16x8 ka[4], kb[4];
; #pragma unroll
;   for (int d0 = 0; d0 < 4; ++d0) { const int cb = (d0 * 16 + hi * 8) * 2;
;     ka[d0] = *reinterpret_cast<const bf16x8*>(Ks + KSWZ64(r32, cb)); kb[d0] = *reinterpret_cast<const bf16x8*>(Ks + KSWZ64(32 + r32, cb)); }
;   asm volatile("s_waitcnt lgkmcnt(0)" ::: "memory"); SBAR();
;   p0 = f32x16{}; p1 = f32x16{};
; #pragma unroll
;   for (int d0 = 0; d0 < 4; ++d0) {
;     p0 = __builtin_amdgcn_mfma_f32_32x32x16_bf16(ka[d0], qr[d0], p0, 0, 0, 0);
;     p1 = __builtin_amdgcn_mfma_f32_32x32x16_bf16(kb[d0], qr[d0], p1, 0, 0, 0); }
; template <bool GRPB> __device__ __forceinline__ void attn_pass(const float mbK, const float bmax2, const int pass, float* __restrict__ scr, bf16* __restrict__ mixrow, const float lam, const float* __restrict__ gsub, const float one_m_li, ...
;     ...
;     __syncthreads(); SWRITE(bm1, 0);
;     RESC(alB);
;     { const int tmp = bm1; bm1 = b0; b0 = bp1; bp1 = tmp; }
;     HSTEP(pA0, pA1, mnA, alA, pB0, pB1, alB, (t + 1) * KVBLK, if (t + 3 < NT) SLOAD(0, (t + 3) * KVBLK));
.LBB0_357:
	s_add_i32 s0, s4, 0
	v_exp_f32_e32 v230, v80
	v_add_u32_e32 v80, s0, v181
	s_barrier
	s_waitcnt vmcnt(2)
	ds_write_b128 v80, v[168:171]
	v_add_u32_e32 v80, s0, v191
	s_waitcnt vmcnt(1)
	ds_write_b128 v80, v[172:175]
	v_lshl_add_u32 v80, s61, 13, v200
	v_exp_f32_e32 v231, v81
	v_exp_f32_e32 v244, v82
	v_exp_f32_e32 v245, v83
	v_exp_f32_e32 v246, v84
	v_exp_f32_e32 v247, v85
	v_exp_f32_e32 v248, v86
	v_exp_f32_e32 v249, v87
	v_exp_f32_e32 v250, v88
	v_exp_f32_e32 v251, v89
	v_exp_f32_e32 v235, v90
	v_exp_f32_e32 v237, v91
	v_exp_f32_e32 v238, v92
	v_exp_f32_e32 v234, v93
	v_exp_f32_e32 v196, v94
	v_exp_f32_e32 v197, v95
	s_waitcnt vmcnt(0)
	ds_write_b128 v80, v[176:179] offset:49152
	s_lshl_b32 s0, s63, 13
	s_add_i32 s0, s0, 0
	v_add_u32_e32 v84, s0, v202
	v_add_u32_e32 v92, s0, v205
	v_add_u32_e32 v96, s0, v207
	ds_read_b128 v[80:83], v84 offset:49152
	ds_read_b128 v[84:87], v84 offset:53248
	ds_read_b128 v[88:91], v92 offset:49152
	ds_read_b128 v[92:95], v92 offset:53248
	ds_read_b128 v[218:221], v96 offset:49152
	ds_read_b128 v[222:225], v96 offset:53248
	v_add_u32_e32 v96, s0, v208
	ds_read_b128 v[226:229], v96 offset:49152
	ds_read_b128 v[240:243], v96 offset:53248
	s_waitcnt lgkmcnt(0)
	s_waitcnt lgkmcnt(7)
	v_mfma_f32_32x32x16_bf16 v[112:127], v[80:83], v[164:167], 0
	v_add_f32_e32 v80, 0, v230
	v_add_f32_e32 v80, v231, v80
	v_add_f32_e32 v80, v244, v80
	v_add_f32_e32 v80, v245, v80
	v_add_f32_e32 v80, v246, v80
	v_add_f32_e32 v80, v247, v80
	v_add_f32_e32 v80, v248, v80
	s_waitcnt lgkmcnt(6)
	v_mfma_f32_32x32x16_bf16 v[96:111], v[84:87], v[164:167], 0
	v_add_f32_e32 v80, v249, v80
	v_add_f32_e32 v80, v250, v80
	v_add_f32_e32 v80, v251, v80
	v_add_f32_e32 v80, v235, v80
	v_add_f32_e32 v80, v237, v80
	v_exp_f32_e32 v128, v128
	v_add_f32_e32 v80, v238, v80
	s_waitcnt lgkmcnt(5)
	v_mfma_f32_32x32x16_bf16 v[112:127], v[88:91], v[160:163], v[112:127]
	v_exp_f32_e32 v129, v129
	v_add_f32_e32 v80, v234, v80
	v_exp_f32_e32 v130, v130
	v_add_f32_e32 v80, v196, v80
	v_exp_f32_e32 v131, v131
	v_add_f32_e32 v80, v197, v80
	v_exp_f32_e32 v132, v132
	s_waitcnt lgkmcnt(4)
	v_mfma_f32_32x32x16_bf16 v[96:111], v[92:95], v[160:163], v[96:111]
	v_add_f32_e32 v80, v128, v80
	v_exp_f32_e32 v133, v133
	v_add_f32_e32 v80, v129, v80
	v_exp_f32_e32 v134, v134
	v_add_f32_e32 v80, v130, v80
	v_exp_f32_e32 v135, v135
	v_add_f32_e32 v80, v131, v80
	s_waitcnt lgkmcnt(3)
	v_mfma_f32_32x32x16_bf16 v[112:127], v[218:221], v[156:159], v[112:127]
	v_exp_f32_e32 v136, v136
	v_add_f32_e32 v80, v132, v80
	v_exp_f32_e32 v137, v137
	v_add_f32_e32 v80, v133, v80
	v_exp_f32_e32 v138, v138
	v_add_f32_e32 v80, v134, v80
	v_exp_f32_e32 v139, v139
	s_waitcnt lgkmcnt(2)
	v_mfma_f32_32x32x16_bf16 v[96:111], v[222:225], v[156:159], v[96:111]
	v_add_f32_e32 v80, v135, v80
	v_exp_f32_e32 v140, v140
	v_add_f32_e32 v80, v136, v80
	v_exp_f32_e32 v141, v141
	v_add_f32_e32 v80, v137, v80
	v_exp_f32_e32 v142, v142
	v_add_f32_e32 v80, v138, v80
	s_waitcnt lgkmcnt(1)
	v_mfma_f32_32x32x16_bf16 v[112:127], v[226:229], v[152:155], v[112:127]
	v_exp_f32_e32 v143, v143
	v_add_f32_e32 v80, v139, v80
	v_add_f32_e32 v80, v140, v80
	v_add_f32_e32 v80, v141, v80
	v_add_f32_e32 v80, v142, v80
	v_add_f32_e32 v218, v143, v80
	v_mov_b32_e32 v219, v218
	s_waitcnt lgkmcnt(0)
	v_mfma_f32_32x32x16_bf16 v[96:111], v[240:243], v[152:155], v[96:111]
	v_cvt_pk_bf16_f32 v80, v230, v231
	v_cvt_pk_bf16_f32 v81, v244, v245
	v_cvt_pk_bf16_f32 v82, v246, v247
	v_cvt_pk_bf16_f32 v83, v248, v249
	v_cvt_pk_bf16_f32 v84, v250, v251
	v_cvt_pk_bf16_f32 v85, v235, v237
	v_cvt_pk_bf16_f32 v86, v238, v234
	v_cvt_pk_bf16_f32 v87, v196, v197
	v_cvt_pk_bf16_f32 v88, v128, v129
	v_cvt_pk_bf16_f32 v89, v130, v131
	v_cvt_pk_bf16_f32 v90, v132, v133
	v_cvt_pk_bf16_f32 v91, v134, v135
	v_cvt_pk_bf16_f32 v92, v136, v137
	v_cvt_pk_bf16_f32 v93, v138, v139
	v_cvt_pk_bf16_f32 v94, v140, v141
	v_cvt_pk_bf16_f32 v95, v142, v143
	v_permlane32_swap_b32_e32 v218, v219
	v_permlane32_swap_b32_e32 v80, v82
	v_permlane32_swap_b32_e32 v81, v83
	v_permlane32_swap_b32_e32 v84, v86
	v_permlane32_swap_b32_e32 v85, v87
	v_permlane32_swap_b32_e32 v88, v90
	v_permlane32_swap_b32_e32 v89, v91
	v_permlane32_swap_b32_e32 v92, v94
	v_permlane32_swap_b32_e32 v93, v95
	s_cmp_lt_u32 s64, 61
	s_cselect_b64 s[0:1], -1, 0
	s_cmp_gt_u32 s64, 60
	s_cbranch_scc1 .LBB0_359
	s_add_u32 s74, s70, 0x18e00000
	s_addc_u32 s75, s71, 0
	global_load_dwordx4 v[168:171], v182, s[74:75] offset:2048
	s_add_u32 s74, s70, 0x18e40000
	s_addc_u32 s75, s71, 0
	global_load_dwordx4 v[172:175], v182, s[74:75] offset:2048
	s_add_u32 s74, s72, 0x18e00000
	s_addc_u32 s75, s73, 0
	global_load_dwordx4 v[176:179], v184, s[74:75] offset:1024

; #define SLOAD(i, k0) do { sr_[i].vs0 = *(const GAS bf16x8*)(&Vh[(long)((k0) + sr) * LDK + sc]); sr_[i].vs1 = *(const GAS bf16x8*)(&Vh[(long)((k0) + 32 + sr) * LDK + sc]); \
;     sr_[i].ks0 = *(const GAS bf16x8*)(&Kh[(long)((k0) + kr) * LDK + kc]); } while (0)
; #define SWRITE(b, i) do { *(bf16x8*)(V_lds + (b) * SHM_V + vst0) = sr_[i].vs0; *(bf16x8*)(V_lds + (b) * SHM_V + vst1) = sr_[i].vs1; \
;     *(bf16x8*)(K_lds + (b) * SHM_K + kst) = sr_[i].ks0; } while (0)
; #define RESC(a) do { if (__any((a) < 1.f)) { if (hi == 0) al_l[r32] = (a); asm volatile("s_waitcnt lgkmcnt(0)" ::: "memory"); \
;     _Pragma("unroll") for (int d = 0; d < 4; ++d) _Pragma("unroll") for (int r = 0; r < 16; ++r) o[d][r] *= al_l[crow(r, hi)]; } } while (0)
; template <bool GRPB> __device__ __forceinline__ void attn_pass(const float mbK, const float bmax2, const int pass, float* __restrict__ scr, bf16* __restrict__ mixrow, const float lam, const float* __restrict__ gsub, const float one_m_li, ...
;     ...
;   for (int t = 1; t + 1 < NT; t += 2) {
;     HSTEP(pB0, pB1, mnB, alB, pA0, pA1, alA, t * KVBLK, SLOAD(0, (t + 2) * KVBLK));
;     __syncthreads(); SWRITE(bm1, 0);
;     RESC(alB);
;     { const int tmp = bm1; bm1 = b0; b0 = bp1; bp1 = tmp; }
;     HSTEP(pA0, pA1, mnA, alA, pB0, pB1, alB, (t + 1) * KVBLK, if (t + 3 < NT) SLOAD(0, (t + 3) * KVBLK));
;     __syncthreads(); if (t + 3 < NT) SWRITE(bm1, 0);
;     RESC(alA);
;     { const int tmp = bm1; bm1 = b0; b0 = bp1; bp1 = tmp; }
.LBB0_363:
	s_andn2_b64 vcc, exec, s[0:1]
	s_mov_b64 s[0:1], -1
	s_barrier
	s_cbranch_vccnz .LBB0_365
	s_add_i32 s0, s4, 0
	v_add_u32_e32 v97, s0, v191
	v_add_u32_e32 v98, s0, v181
	s_add_u32 s70, s70, s16
	s_addc_u32 s71, s71, s17
	s_add_u32 s72, s72, s16
	s_addc_u32 s73, s73, s17
	s_addk_i32 s62, 0x80
	v_add_u32_e32 v215, 0x200, v215
	s_add_i32 s64, s64, 2
	s_mov_b64 s[0:1], 0
	v_add_u32_e32 v96, s36, v192
	s_waitcnt vmcnt(2)
	ds_write_b128 v98, v[168:171]
	s_waitcnt vmcnt(1)
	ds_write_b128 v97, v[172:175]
	s_waitcnt vmcnt(0)
	ds_write_b128 v96, v[176:179] offset:49152

; #define GAS __attribute__((address_space(1)))
; __device__ __forceinline__ float bf2f(unsigned short b) { return __uint_as_float(((unsigned)b) << 16); }
; __device__ __forceinline__ int v_st(int k, int c) { const int kk = (k & ~0xC) | ((k & 4) << 1) | ((k & 8) >> 1); return ((kk >> 3) * 4 + (c >> 5)) * 512 + ((kk & 7) * 32 + (c & 31)) * 2; }
; __device__ __forceinline__ int v_rd_base(int lane) { return ((lane & 3) << 3) | (((lane >> 2) & 3) << 6) | (((lane >> 4) & 1) << 5) | (((lane >> 5) & 1) << 8); }
; template <bool GRPB> __device__ __forceinline__ void attn_pass(const float mbK, const float bmax2, const int pass, float* __restrict__ scr, bf16* __restrict__ mixrow, const float lam, const float* __restrict__ gsub, const float one_m_li, ...
;     ...
;   float m_reg, l_reg = 0; bf16x8 qr[4]; f32x16 o[4];
; #pragma unroll
;   for (int d = 0; d < 4; ++d) o[d] = f32x16{};
;   const bf16* Qw = Qb + (long)(wid * 32 + r32) * LDK + hi * 8;
; #pragma unroll
;   for (int d0 = 0; d0 < 4; ++d0) qr[d0] = *(const GAS bf16x8*)(Qw + d0 * 16);
;   { float qs = 0.f;
; #pragma unroll
;     for (int d0 = 0; d0 < 4; ++d0)
; #pragma unroll
;       for (int j = 0; j < 8; ++j) { const float v = bf2f((unsigned short)qr[d0][j]); qs = fmaf(v, v, qs); }
;     { auto rr = __builtin_amdgcn_permlane32_swap(__float_as_uint(qs), __float_as_uint(qs), false, false); qs = __uint_as_float(rr[0]) + __uint_as_float(rr[1]); }
;     m_reg = __builtin_sqrtf(qs) * mbK + bmax2 + 0.25f; }
;   const int sr = tid >> 4, sc = (tid & 15) * 8, vst0 = v_st(sr, sc), vst1 = v_st(32 + sr, sc);
;   const int kr = tid >> 3, kc = (tid & 7) * 8, kst = KSWZ64(kr, kc * 2);
;   const int vb0 = (int)(uintptr_t)V_lds + v_rd_base(lane);
;   struct { bf16x8 vs0, vs1, ks0; } sr_[2];
;     ...
;   f32x16 pA0, pA1, pB0, pB1; float mnA, mnB, alA, alB; bf16x8 pa0, pa1, pa2, pa3; constexpr int NT = SEQ / KVBLK;
;   __syncthreads();
;   SLOAD(0, 0); SLOAD(1, KVBLK); asm volatile("s_waitcnt vmcnt(0)" ::: "memory"); SWRITE(0, 0); SWRITE(1, 1);
;   SLOAD(0, 2 * KVBLK); asm volatile("s_waitcnt vmcnt(0)" ::: "memory"); SWRITE(2, 0); __syncthreads();
;   qkt(pA0, pA1, K_lds, qr, r32, hi); partialSM(pA0, pA1, m_reg, mnA, alA, 0, qpos, qw, hi, tb2, cL, cR);
;   int bm1 = 0, b0 = 1, bp1 = 2;
.LBB0_377:
	v_and_b32_e32 v201, 63, v146
	s_nop 7
	v_lshlrev_b32_e32 v1, 4, v201
	v_lshlrev_b32_e32 v0, 3, v201
	v_and_b32_e32 v1, 0xc0, v1
	v_lshlrev_b32_e32 v2, 1, v201
	v_and_or_b32 v1, v0, 24, v1
	v_and_b32_e32 v2, 32, v2
	v_and_b32_e32 v0, 0x100, v0
	v_or3_b32 v214, v1, v2, v0
	v_and_b32_e32 v2, 15, v146
	v_lshl_add_u64 v[0:1], s[48:49], 0, v[48:49]
	v_lshlrev_b32_e32 v2, 4, v2
	v_mov_b32_e32 v3, v144
	v_lshl_add_u64 v[0:1], v[0:1], 0, v[2:3]
	v_and_b32_e32 v2, 7, v146
	v_exp_f32_e32 v173, v32
	v_exp_f32_e32 v175, v33
	v_exp_f32_e32 v171, v34
	v_exp_f32_e32 v174, v35
	v_exp_f32_e32 v169, v36
	v_exp_f32_e32 v172, v37
	v_exp_f32_e32 v168, v38
	v_exp_f32_e32 v170, v39
	v_exp_f32_e32 v133, v40
	v_exp_f32_e32 v135, v41
	v_exp_f32_e32 v131, v42
	v_exp_f32_e32 v134, v43
	v_exp_f32_e32 v129, v44
	v_exp_f32_e32 v132, v45
	v_exp_f32_e32 v128, v46
	v_exp_f32_e32 v130, v47
	v_lshl_add_u64 v[182:183], s[18:19], 0, v[0:1]
	v_lshl_add_u64 v[0:1], s[48:49], 0, v[50:51]
	v_lshlrev_b32_e32 v2, 4, v2
	s_cmp_lg_u32 0, -1
	v_lshl_add_u64 v[0:1], v[0:1], 0, v[2:3]
	s_cselect_b32 s1, 0, 0
	v_lshl_add_u64 v[184:185], s[18:19], 0, v[0:1]
	v_sub_u32_e32 v0, v180, v52
	v_mov_b32_e32 v191, 0
	s_mov_b32 s45, 1
	s_mov_b32 s0, 0
	v_add_u32_e32 v147, s1, v214
	v_mov_b32_e32 v65, v64
	v_mov_b32_e32 v66, v64
	v_mov_b32_e32 v67, v64
	v_mov_b32_e32 v68, v64
	v_mov_b32_e32 v69, v64
	v_mov_b32_e32 v70, v64
	v_mov_b32_e32 v71, v64
	v_mov_b32_e32 v72, v64
	s_sub_i32 s48, 0x7f, s39
	s_mov_b32 s49, 2
	v_add_u32_e32 v216, s59, v0
	s_mov_b32 s50, 1
	v_mov_b32_e32 v0, 0
	v_mov_b32_e32 v1, v191
	v_mov_b32_e32 v2, v191
	v_mov_b32_e32 v3, v191
	v_mov_b32_e32 v4, v191
	v_mov_b32_e32 v5, v191
	v_mov_b32_e32 v6, v191
	v_mov_b32_e32 v7, v191
	v_mov_b32_e32 v8, v191
	v_mov_b32_e32 v9, v191
	v_mov_b32_e32 v10, v191
	v_mov_b32_e32 v11, v191
	v_mov_b32_e32 v12, v191
	v_mov_b32_e32 v13, v191
	v_mov_b32_e32 v14, v191
	v_mov_b32_e32 v15, v191
	v_mov_b32_e32 v16, 0
	v_mov_b32_e32 v17, v191
	v_mov_b32_e32 v18, v191
	v_mov_b32_e32 v19, v191
	v_mov_b32_e32 v20, v191
	v_mov_b32_e32 v21, v191
	v_mov_b32_e32 v22, v191
	v_mov_b32_e32 v23, v191
	v_mov_b32_e32 v24, v191
	v_mov_b32_e32 v25, v191
	v_mov_b32_e32 v26, v191
	v_mov_b32_e32 v27, v191
	v_mov_b32_e32 v28, v191
	v_mov_b32_e32 v29, v191
	v_mov_b32_e32 v30, v191
	v_mov_b32_e32 v31, v191
	v_mov_b32_e32 v32, 0
	v_mov_b32_e32 v33, v191
	v_mov_b32_e32 v34, v191
	v_mov_b32_e32 v35, v191
	v_mov_b32_e32 v36, v191
	v_mov_b32_e32 v37, v191
	v_mov_b32_e32 v38, v191
	v_mov_b32_e32 v39, v191
	v_mov_b32_e32 v40, v191
	v_mov_b32_e32 v41, v191
	v_mov_b32_e32 v42, v191
	v_mov_b32_e32 v43, v191
	v_mov_b32_e32 v44, v191
	v_mov_b32_e32 v45, v191
	v_mov_b32_e32 v46, v191
	v_mov_b32_e32 v47, v191
	v_mov_b32_e32 v48, 0
	v_mov_b32_e32 v49, v191
	v_mov_b32_e32 v50, v191
	v_mov_b32_e32 v51, v191
	v_mov_b32_e32 v52, v191
	v_mov_b32_e32 v53, v191
	v_mov_b32_e32 v54, v191
	v_mov_b32_e32 v55, v191
	v_mov_b32_e32 v56, v191
	v_mov_b32_e32 v57, v191
	v_mov_b32_e32 v58, v191
	v_mov_b32_e32 v59, v191
	v_mov_b32_e32 v60, v191
	v_mov_b32_e32 v61, v191
	v_mov_b32_e32 v62, v191
	v_mov_b32_e32 v63, v191
	v_mov_b32_e32 v75, v64
	v_mov_b32_e32 v74, v64
	v_mov_b32_e32 v73, v64
	v_mov_b32_e32 v78, v64
	v_mov_b32_e32 v79, v64
	v_mov_b32_e32 v76, v64
	v_mov_b32_e32 v77, v64
	s_nop 0
	v_readfirstlane_b32 s70, v182
	v_readfirstlane_b32 s71, v183
	v_readfirstlane_b32 s72, v184
	v_readfirstlane_b32 s73, v185
	s_nop 1
	v_subrev_u32_e32 v182, s70, v182
	v_subrev_u32_e32 v184, s72, v184
	s_add_u32 s70, s70, s2
	s_addc_u32 s71, s71, s3
	s_add_u32 s72, s72, s2
	s_addc_u32 s73, s73, s3
.LBB0_378:
	s_mov_b32 s51, s45
	s_mov_b32 s45, s0
	s_lshl_b32 s0, s51, 13
	s_add_i32 s36, s0, 0
	v_add_u32_e32 v100, s36, v203
	v_add_u32_e32 v104, s36, v206
	ds_read_b128 v[96:99], v100 offset:49152
	ds_read_b128 v[100:103], v100 offset:53248
	ds_read_b128 v[136:139], v104 offset:49152
	ds_read_b128 v[140:143], v104 offset:53248
	v_add_u32_e32 v104, s36, v208
	s_waitcnt vmcnt(0)
	ds_read_b128 v[176:179], v104 offset:49152
	ds_read_b128 v[186:189], v104 offset:53248
	v_add_u32_e32 v104, s36, v209
	ds_read_b128 v[218:221], v104 offset:49152
	ds_read_b128 v[222:225], v104 offset:53248
	s_waitcnt lgkmcnt(0)
	v_exp_f32_e32 v196, v80
	v_add_f32_e32 v80, 0, v173
	v_add_f32_e32 v80, v175, v80
	s_waitcnt lgkmcnt(7)
	v_mfma_f32_32x32x16_bf16 v[112:127], v[96:99], v[164:167], 0
	v_add_f32_e32 v80, v171, v80
	v_add_f32_e32 v80, v174, v80
	v_add_f32_e32 v80, v169, v80
	v_add_f32_e32 v80, v172, v80
	v_add_f32_e32 v80, v168, v80
	v_add_f32_e32 v80, v170, v80
	v_add_f32_e32 v80, v133, v80
	s_waitcnt lgkmcnt(6)
	v_mfma_f32_32x32x16_bf16 v[96:111], v[100:103], v[164:167], 0
	v_add_f32_e32 v80, v135, v80
	v_add_f32_e32 v80, v131, v80
	v_add_f32_e32 v80, v134, v80
	v_add_f32_e32 v80, v129, v80
	v_exp_f32_e32 v197, v81
	v_add_f32_e32 v80, v132, v80
	v_exp_f32_e32 v226, v82
	s_waitcnt lgkmcnt(5)
	v_mfma_f32_32x32x16_bf16 v[112:127], v[136:139], v[160:163], v[112:127]
	v_add_f32_e32 v80, v128, v80
	v_exp_f32_e32 v227, v83
	v_add_f32_e32 v80, v130, v80
	v_exp_f32_e32 v228, v84
	v_add_f32_e32 v80, v196, v80
	v_exp_f32_e32 v229, v85
	v_add_f32_e32 v80, v197, v80
	s_waitcnt lgkmcnt(4)
	v_mfma_f32_32x32x16_bf16 v[96:111], v[140:143], v[160:163], v[96:111]
	v_exp_f32_e32 v230, v86
	v_add_f32_e32 v80, v226, v80
	v_exp_f32_e32 v231, v87
	v_add_f32_e32 v80, v227, v80
	v_exp_f32_e32 v234, v88
	v_add_f32_e32 v80, v228, v80
	v_exp_f32_e32 v235, v89
	s_waitcnt lgkmcnt(3)
	v_mfma_f32_32x32x16_bf16 v[112:127], v[176:179], v[156:159], v[112:127]
	v_add_f32_e32 v80, v229, v80
	v_exp_f32_e32 v237, v90
	v_add_f32_e32 v80, v230, v80
	v_exp_f32_e32 v238, v91
	v_add_f32_e32 v80, v231, v80
	v_exp_f32_e32 v240, v92
	v_add_f32_e32 v80, v234, v80
	s_waitcnt lgkmcnt(2)
; __device__ __forceinline__ void finishSM(f32x16& p0, f32x16& p1, float alpha, float& l_reg, bf16x8& pa0, bf16x8& pa1, bf16x8& pa2, bf16x8& pa3) {
; #pragma unroll
;   for (int r = 0; r < 16; ++r) p1[r] = __builtin_amdgcn_exp2f(p1[r]);
;   float ps = 0;
; #pragma unroll
;   for (int r = 0; r < 16; ++r) ps += p0[r];
; #pragma unroll
;   for (int r = 0; r < 16; ++r) ps += p1[r];
;   { auto rr = __builtin_amdgcn_permlane32_swap(__float_as_uint(ps), __float_as_uint(ps), false, false);
;     ps = __uint_as_float(rr[0]) + __uint_as_float(rr[1]); }
;   l_reg = l_reg * alpha + ps;
;     ...
;   PK4(p0, 0, pa0); PK4(p0, 8, pa1); PK4(p1, 0, pa2); PK4(p1, 8, pa3);
;     ...
; }
; __device__ __forceinline__ void qkt(f32x16& p0, f32x16& p1, const char* Ks, const bf16x8* qr, int r32, int hi) {
;   bf16x8 ka[4], kb[4];
; #pragma unroll
;   for (int d0 = 0; d0 < 4; ++d0) { const int cb = (d0 * 16 + hi * 8) * 2;
;     ka[d0] = *reinterpret_cast<const bf16x8*>(Ks + KSWZ64(r32, cb)); kb[d0] = *reinterpret_cast<const bf16x8*>(Ks + KSWZ64(32 + r32, cb)); }
;   asm volatile("s_waitcnt lgkmcnt(0)" ::: "memory"); SBAR();
;   p0 = f32x16{}; p1 = f32x16{};
; #pragma unroll
;   for (int d0 = 0; d0 < 4; ++d0) {
;     p0 = __builtin_amdgcn_mfma_f32_32x32x16_bf16(ka[d0], qr[d0], p0, 0, 0, 0);
;     p1 = __builtin_amdgcn_mfma_f32_32x32x16_bf16(kb[d0], qr[d0], p1, 0, 0, 0); }
; }
; __device__ __forceinline__ int v_st(int k, int c) { const int kk = (k & ~0xC) | ((k & 4) << 1) | ((k & 8) >> 1); return ((kk >> 3) * 4 + (c >> 5)) * 512 + ((kk & 7) * 32 + (c & 31)) * 2; }
; __device__ __forceinline__ int v_rd_base(int lane) { return ((lane & 3) << 3) | (((lane >> 2) & 3) << 6) | (((lane >> 4) & 1) << 5) | (((lane >> 5) & 1) << 8); }
; template <int OFF> __device__ __forceinline__ s16x4 tr_read(int vb) {
;   s16x4 r; asm volatile("ds_read_b64_tr_b16 %0, %1 offset:%2" : "=&v"(r) : "v"(vb), "i"(OFF) : "memory"); return r;
; }
; template <int D0> __device__ __forceinline__ void pv_one(f32x16& od, int vb, bf16x8 pa0, bf16x8 pa1, bf16x8 pa2, bf16x8 pa3) {
;   const s16x4 l0 = tr_read<v_rd_off(D0, 0, 0)>(vb), h0 = tr_read<v_rd_off(D0, 0, 1)>(vb), l1 = tr_read<v_rd_off(D0, 1, 0)>(vb), h1 = tr_read<v_rd_off(D0, 1, 1)>(vb);
;   const s16x4 l2 = tr_read<v_rd_off(D0, 2, 0)>(vb), h2 = tr_read<v_rd_off(D0, 2, 1)>(vb), l3 = tr_read<v_rd_off(D0, 3, 0)>(vb), h3 = tr_read<v_rd_off(D0, 3, 1)>(vb);
	v_mfma_f32_32x32x16_bf16 v[96:111], v[186:189], v[156:159], v[96:111]
	v_exp_f32_e32 v241, v93
	v_add_f32_e32 v80, v235, v80
	v_exp_f32_e32 v242, v94
	v_add_f32_e32 v80, v237, v80
	v_exp_f32_e32 v95, v95
	v_add_f32_e32 v80, v238, v80
	v_add_f32_e32 v80, v240, v80
	s_waitcnt lgkmcnt(1)
	v_mfma_f32_32x32x16_bf16 v[112:127], v[218:221], v[152:155], v[112:127]
	v_add_f32_e32 v80, v241, v80
	v_add_f32_e32 v80, v242, v80
	v_add_f32_e32 v217, v95, v80
	v_mov_b32_e32 v218, v217
	v_cvt_pk_bf16_f32 v80, v173, v175
	v_cvt_pk_bf16_f32 v81, v171, v174
	v_cvt_pk_bf16_f32 v82, v169, v172
	s_waitcnt lgkmcnt(0)
	v_mfma_f32_32x32x16_bf16 v[96:111], v[222:225], v[152:155], v[96:111]
	v_cvt_pk_bf16_f32 v83, v168, v170
	v_cvt_pk_bf16_f32 v84, v133, v135
	v_cvt_pk_bf16_f32 v85, v131, v134
	v_cvt_pk_bf16_f32 v86, v129, v132
	v_cvt_pk_bf16_f32 v87, v128, v130
	v_cvt_pk_bf16_f32 v88, v196, v197
	v_cvt_pk_bf16_f32 v89, v226, v227
	v_cvt_pk_bf16_f32 v90, v228, v229
	v_cvt_pk_bf16_f32 v91, v230, v231
	v_cvt_pk_bf16_f32 v92, v234, v235
	v_cvt_pk_bf16_f32 v93, v237, v238
	v_cvt_pk_bf16_f32 v94, v240, v241
	v_cvt_pk_bf16_f32 v95, v242, v95
	v_permlane32_swap_b32_e32 v217, v218
	v_permlane32_swap_b32_e32 v80, v82
	v_permlane32_swap_b32_e32 v81, v83
	v_permlane32_swap_b32_e32 v84, v86
	v_permlane32_swap_b32_e32 v85, v87
	v_permlane32_swap_b32_e32 v88, v90
	v_permlane32_swap_b32_e32 v89, v91
	v_permlane32_swap_b32_e32 v92, v94
	v_permlane32_swap_b32_e32 v93, v95
	s_mov_b32 s0, 0x18dc0000
	s_add_u32 s74, s70, s15
	s_addc_u32 s75, s71, 0
	global_load_dwordx4 v[168:171], v182, s[74:75] offset:2048
	s_add_u32 s74, s70, s0
	s_addc_u32 s75, s71, 0
	global_load_dwordx4 v[172:175], v182, s[74:75] offset:2048
	s_add_u32 s74, s72, s15
	s_addc_u32 s75, s73, 0
	global_load_dwordx4 v[176:179], v184, s[74:75] offset:1152
	s_lshl_b32 s4, s45, 14
	v_add_u32_e32 v196, s4, v147
	ds_read_b64_tr_b16 v[128:129], v196 offset:0
	ds_read_b64_tr_b16 v[130:131], v196 offset:0x800
	ds_read_b64_tr_b16 v[132:133], v196 offset:0x1000
	ds_read_b64_tr_b16 v[134:135], v196 offset:0x1800
	ds_read_b64_tr_b16 v[136:137], v196 offset:0x2000
	ds_read_b64_tr_b16 v[138:139], v196 offset:0x2800
	ds_read_b64_tr_b16 v[140:141], v196 offset:0x3000
	ds_read_b64_tr_b16 v[142:143], v196 offset:0x3800
	s_waitcnt lgkmcnt(0)
	s_nop 0
	v_mfma_f32_32x32x16_bf16 v[0:15], v[80:83], v[128:131], v[0:15]
	ds_read_b64_tr_b16 v[128:129], v196 offset:0x200
	ds_read_b64_tr_b16 v[130:131], v196 offset:0xa00
	v_mfma_f32_32x32x16_bf16 v[0:15], v[84:87], v[132:135], v[0:15]
	ds_read_b64_tr_b16 v[132:133], v196 offset:0x1200
	ds_read_b64_tr_b16 v[134:135], v196 offset:0x1a00
	v_mfma_f32_32x32x16_bf16 v[0:15], v[88:91], v[136:139], v[0:15]
	ds_read_b64_tr_b16 v[136:137], v196 offset:0x2200
	ds_read_b64_tr_b16 v[138:139], v196 offset:0x2a00
	v_mfma_f32_32x32x16_bf16 v[0:15], v[92:95], v[140:143], v[0:15]
	ds_read_b64_tr_b16 v[140:141], v196 offset:0x3200
	ds_read_b64_tr_b16 v[142:143], v196 offset:0x3a00
	s_waitcnt lgkmcnt(0)
	v_mfma_f32_32x32x16_bf16 v[16:31], v[80:83], v[128:131], v[16:31]
	ds_read_b64_tr_b16 v[128:129], v196 offset:0x400
	ds_read_b64_tr_b16 v[130:131], v196 offset:0xc00
	v_mfma_f32_32x32x16_bf16 v[16:31], v[84:87], v[132:135], v[16:31]
	ds_read_b64_tr_b16 v[132:133], v196 offset:0x1400
	ds_read_b64_tr_b16 v[134:135], v196 offset:0x1c00
	v_mfma_f32_32x32x16_bf16 v[16:31], v[88:91], v[136:139], v[16:31]
	ds_read_b64_tr_b16 v[136:137], v196 offset:0x2400
	ds_read_b64_tr_b16 v[138:139], v196 offset:0x2c00
	v_mfma_f32_32x32x16_bf16 v[16:31], v[92:95], v[140:143], v[16:31]
	ds_read_b64_tr_b16 v[140:141], v196 offset:0x3400
	ds_read_b64_tr_b16 v[142:143], v196 offset:0x3c00
	s_waitcnt lgkmcnt(0)
	v_mfma_f32_32x32x16_bf16 v[32:47], v[80:83], v[128:131], v[32:47]
	ds_read_b64_tr_b16 v[128:129], v196 offset:0x600
	ds_read_b64_tr_b16 v[130:131], v196 offset:0xe00
	v_mfma_f32_32x32x16_bf16 v[32:47], v[84:87], v[132:135], v[32:47]
	ds_read_b64_tr_b16 v[132:133], v196 offset:0x1600
	ds_read_b64_tr_b16 v[134:135], v196 offset:0x1e00
	v_mfma_f32_32x32x16_bf16 v[32:47], v[88:91], v[136:139], v[32:47]
	ds_read_b64_tr_b16 v[136:137], v196 offset:0x2600
	ds_read_b64_tr_b16 v[138:139], v196 offset:0x2e00
	v_mfma_f32_32x32x16_bf16 v[32:47], v[92:95], v[140:143], v[32:47]
	ds_read_b64_tr_b16 v[140:141], v196 offset:0x3600
	ds_read_b64_tr_b16 v[142:143], v196 offset:0x3e00
	s_waitcnt lgkmcnt(0)
	v_mfma_f32_32x32x16_bf16 v[48:63], v[80:83], v[128:131], v[48:63]
	s_add_i32 s5, s48, 0xffffff47
	s_mov_b64 s[0:1], -1
	s_cmp_gt_u32 s5, 0xfffffeec
	v_mfma_f32_32x32x16_bf16 v[48:63], v[84:87], v[132:135], v[48:63]
	v_mfma_f32_32x32x16_bf16 v[48:63], v[88:91], v[136:139], v[48:63]
	v_mfma_f32_32x32x16_bf16 v[48:63], v[92:95], v[140:143], v[48:63]
	s_cbranch_scc0 .LBB0_380
; __device__ __forceinline__ void partialSM(f32x16& p0, f32x16& p1, float& m_reg, float& mn, float& alpha, int kt0, int qpos, int qw, int hi, const float* tb2, float cL, float cR) {
;     ...
;     const float* tp = tb2 + (kt0 - qpos + 192 + 4 * hi);
; #pragma unroll
;     for (int r4 = 0; r4 < 4; ++r4) {
;       float ta[4], tb[4];
; #pragma unroll
;       for (int i = 0; i < 4; ++i) { ta[i] = tp[8 * r4 + i] - m_reg; tb[i] = tp[32 + 8 * r4 + i] - m_reg; }
; #pragma unroll
;       for (int i = 0; i < 4; ++i) { p0[4 * r4 + i] = fmaf(p0[4 * r4 + i], C1, ta[i]); p1[4 * r4 + i] = fmaf(p1[4 * r4 + i], C1, tb[i]); }
;       asm volatile("" ::: "memory");
;     }
	ds_read2_b32 v[80:81], v216 offset1:1
	ds_read2_b32 v[128:129], v216 offset0:32 offset1:33
	ds_read2_b32 v[130:131], v216 offset0:34 offset1:35
	ds_read2_b32 v[82:83], v216 offset0:2 offset1:3
	ds_read2_b32 v[84:85], v216 offset0:8 offset1:9
	ds_read2_b32 v[132:133], v216 offset0:40 offset1:41
	ds_read2_b32 v[134:135], v216 offset0:42 offset1:43
	ds_read2_b32 v[86:87], v216 offset0:10 offset1:11
	ds_read2_b32 v[88:89], v216 offset0:16 offset1:17
	ds_read2_b32 v[136:137], v216 offset0:48 offset1:49
	ds_read2_b32 v[138:139], v216 offset0:50 offset1:51
	ds_read2_b32 v[90:91], v216 offset0:18 offset1:19
	ds_read2_b32 v[92:93], v216 offset0:24 offset1:25
	ds_read2_b32 v[94:95], v216 offset0:26 offset1:27
	ds_read2_b32 v[140:141], v216 offset0:56 offset1:57
	ds_read2_b32 v[142:143], v216 offset0:58 offset1:59
	s_waitcnt lgkmcnt(3)
	v_sub_f32_e32 v93, v93, v79
	v_sub_f32_e32 v92, v92, v78
	s_waitcnt lgkmcnt(2)
	v_sub_f32_e32 v95, v95, v77
	v_sub_f32_e32 v94, v94, v76
	v_sub_f32_e32 v89, v89, v75
	v_sub_f32_e32 v88, v88, v72
	v_sub_f32_e32 v91, v91, v73
	v_sub_f32_e32 v90, v90, v74
	v_sub_f32_e32 v85, v85, v69
	v_sub_f32_e32 v84, v84, v68
	v_sub_f32_e32 v87, v87, v71
	v_sub_f32_e32 v86, v86, v70
	v_sub_f32_e32 v81, v81, v65
	v_sub_f32_e32 v80, v80, v64
	v_sub_f32_e32 v83, v83, v67
	v_sub_f32_e32 v82, v82, v66
	s_waitcnt lgkmcnt(1)
	v_sub_f32_e32 v141, v141, v79
	v_sub_f32_e32 v140, v140, v78
	s_waitcnt lgkmcnt(0)
	v_sub_f32_e32 v143, v143, v77
	v_sub_f32_e32 v142, v142, v76
	v_sub_f32_e32 v137, v137, v75
	v_sub_f32_e32 v136, v136, v72
	v_sub_f32_e32 v139, v139, v73
	v_sub_f32_e32 v138, v138, v74
	v_sub_f32_e32 v133, v133, v69
	v_sub_f32_e32 v132, v132, v68
	v_sub_f32_e32 v135, v135, v71
	v_sub_f32_e32 v134, v134, v70
	v_sub_f32_e32 v129, v129, v65
	v_sub_f32_e32 v128, v128, v64
	v_sub_f32_e32 v131, v131, v67
	v_sub_f32_e32 v130, v130, v66
	v_pk_fma_f32 v[82:83], v[114:115], s[6:7], v[82:83] op_sel_hi:[1,0,1]
	v_pk_fma_f32 v[80:81], v[112:113], s[6:7], v[80:81] op_sel_hi:[1,0,1]
	v_pk_fma_f32 v[86:87], v[118:119], s[6:7], v[86:87] op_sel_hi:[1,0,1]
	v_pk_fma_f32 v[84:85], v[116:117], s[6:7], v[84:85] op_sel_hi:[1,0,1]
	v_pk_fma_f32 v[90:91], v[122:123], s[6:7], v[90:91] op_sel_hi:[1,0,1]
	v_pk_fma_f32 v[88:89], v[120:121], s[6:7], v[88:89] op_sel_hi:[1,0,1]
	v_pk_fma_f32 v[94:95], v[126:127], s[6:7], v[94:95] op_sel_hi:[1,0,1]
	v_pk_fma_f32 v[92:93], v[124:125], s[6:7], v[92:93] op_sel_hi:[1,0,1]
	v_pk_fma_f32 v[130:131], v[98:99], s[6:7], v[130:131] op_sel_hi:[1,0,1]
	v_pk_fma_f32 v[128:129], v[96:97], s[6:7], v[128:129] op_sel_hi:[1,0,1]
	v_pk_fma_f32 v[134:135], v[102:103], s[6:7], v[134:135] op_sel_hi:[1,0,1]
	v_pk_fma_f32 v[132:133], v[100:101], s[6:7], v[132:133] op_sel_hi:[1,0,1]
	v_pk_fma_f32 v[138:139], v[106:107], s[6:7], v[138:139] op_sel_hi:[1,0,1]
	v_pk_fma_f32 v[136:137], v[104:105], s[6:7], v[136:137] op_sel_hi:[1,0,1]
	v_pk_fma_f32 v[142:143], v[110:111], s[6:7], v[142:143] op_sel_hi:[1,0,1]
	v_pk_fma_f32 v[140:141], v[108:109], s[6:7], v[140:141] op_sel_hi:[1,0,1]
	s_mov_b64 s[0:1], 0

; #define SBAR() __builtin_amdgcn_sched_barrier(0)
; #define SLOAD(i, k0) do { sr_[i].vs0 = *(const GAS bf16x8*)(&Vh[(long)((k0) + sr) * LDK + sc]); sr_[i].vs1 = *(const GAS bf16x8*)(&Vh[(long)((k0) + 32 + sr) * LDK + sc]); \
;     sr_[i].ks0 = *(const GAS bf16x8*)(&Kh[(long)((k0) + kr) * LDK + kc]); } while (0)
; __device__ __forceinline__ void partialSM(f32x16& p0, f32x16& p1, float& m_reg, float& mn, float& alpha, int kt0, int qpos, int qw, int hi, const float* tb2, float cL, float cR) {
;     ...
;   for (int r = 0; r < 16; ++r) p0[r] = __builtin_amdgcn_exp2f(p0[r]);
; }
; __device__ __forceinline__ void finishSM(f32x16& p0, f32x16& p1, float alpha, float& l_reg, bf16x8& pa0, bf16x8& pa1, bf16x8& pa2, bf16x8& pa3) {
; #pragma unroll
;   for (int r = 0; r < 16; ++r) p1[r] = __builtin_amdgcn_exp2f(p1[r]);
;   float ps = 0;
; #pragma unroll
;   for (int r = 0; r < 16; ++r) ps += p0[r];
; #pragma unroll
;   for (int r = 0; r < 16; ++r) ps += p1[r];
;   { auto rr = __builtin_amdgcn_permlane32_swap(__float_as_uint(ps), __float_as_uint(ps), false, false);
;     ps = __uint_as_float(rr[0]) + __uint_as_float(rr[1]); }
;   l_reg = l_reg * alpha + ps;
;     ...
;   PK4(p0, 0, pa0); PK4(p0, 8, pa1); PK4(p1, 0, pa2); PK4(p1, 8, pa3);
;     ...
; }
; __device__ __forceinline__ void qkt(f32x16& p0, f32x16& p1, const char* Ks, const bf16x8* qr, int r32, int hi) {
;   bf16x8 ka[4], kb[4];
; #pragma unroll
;   for (int d0 = 0; d0 < 4; ++d0) { const int cb = (d0 * 16 + hi * 8) * 2;
;     ka[d0] = *reinterpret_cast<const bf16x8*>(Ks + KSWZ64(r32, cb)); kb[d0] = *reinterpret_cast<const bf16x8*>(Ks + KSWZ64(32 + r32, cb)); }
;   asm volatile("s_waitcnt lgkmcnt(0)" ::: "memory"); SBAR();
;   p0 = f32x16{}; p1 = f32x16{};
; #pragma unroll
;   for (int d0 = 0; d0 < 4; ++d0) {
;     p0 = __builtin_amdgcn_mfma_f32_32x32x16_bf16(ka[d0], qr[d0], p0, 0, 0, 0);
;     p1 = __builtin_amdgcn_mfma_f32_32x32x16_bf16(kb[d0], qr[d0], p1, 0, 0, 0); }
; template <bool GRPB> __device__ __forceinline__ void attn_pass(const float mbK, const float bmax2, const int pass, float* __restrict__ scr, bf16* __restrict__ mixrow, const float lam, const float* __restrict__ gsub, const float one_m_li, ...
;     ...
;     __syncthreads(); SWRITE(bm1, 0);
;     RESC(alB);
;     { const int tmp = bm1; bm1 = b0; b0 = bp1; bp1 = tmp; }
;     HSTEP(pA0, pA1, mnA, alA, pB0, pB1, alB, (t + 1) * KVBLK, if (t + 3 < NT) SLOAD(0, (t + 3) * KVBLK));
.LBB0_382:
	s_add_i32 s0, s4, 0
	v_exp_f32_e32 v196, v80
	v_add_u32_e32 v80, s0, v193
	s_barrier
	s_waitcnt vmcnt(2)
	ds_write_b128 v80, v[168:171]
	v_add_u32_e32 v80, s0, v194
	s_waitcnt vmcnt(1)
	ds_write_b128 v80, v[172:175]
	v_lshl_add_u32 v80, s45, 13, v200
	v_exp_f32_e32 v197, v81
	v_exp_f32_e32 v234, v82
	v_exp_f32_e32 v235, v83
	v_exp_f32_e32 v237, v84
	v_exp_f32_e32 v238, v85
	v_exp_f32_e32 v244, v86
	v_exp_f32_e32 v245, v87
	v_exp_f32_e32 v246, v88
	v_exp_f32_e32 v247, v89
	v_exp_f32_e32 v248, v90
	v_exp_f32_e32 v249, v91
	v_exp_f32_e32 v250, v92
	v_exp_f32_e32 v251, v93
	v_exp_f32_e32 v198, v94
	v_exp_f32_e32 v199, v95
	s_waitcnt vmcnt(0)
	ds_write_b128 v80, v[176:179] offset:49152
	s_lshl_b32 s0, s49, 13
	s_add_i32 s0, s0, 0
	v_add_u32_e32 v84, s0, v203
	v_add_u32_e32 v92, s0, v206
	v_add_u32_e32 v96, s0, v208
	ds_read_b128 v[80:83], v84 offset:49152
	ds_read_b128 v[84:87], v84 offset:53248
	ds_read_b128 v[88:91], v92 offset:49152
	ds_read_b128 v[92:95], v92 offset:53248
	ds_read_b128 v[220:223], v96 offset:49152
	ds_read_b128 v[224:227], v96 offset:53248
	v_add_u32_e32 v96, s0, v209
	ds_read_b128 v[228:231], v96 offset:49152
	ds_read_b128 v[240:243], v96 offset:53248
	s_waitcnt lgkmcnt(0)
	s_waitcnt lgkmcnt(7)
	v_mfma_f32_32x32x16_bf16 v[112:127], v[80:83], v[164:167], 0
	v_add_f32_e32 v80, 0, v196
	v_add_f32_e32 v80, v197, v80
	v_add_f32_e32 v80, v234, v80
	v_add_f32_e32 v80, v235, v80
	v_add_f32_e32 v80, v237, v80
	v_add_f32_e32 v80, v238, v80
	v_add_f32_e32 v80, v244, v80
	s_waitcnt lgkmcnt(6)
	v_mfma_f32_32x32x16_bf16 v[96:111], v[84:87], v[164:167], 0
	v_add_f32_e32 v80, v245, v80
	v_add_f32_e32 v80, v246, v80
	v_add_f32_e32 v80, v247, v80
	v_add_f32_e32 v80, v248, v80
	v_add_f32_e32 v80, v249, v80
	v_exp_f32_e32 v128, v128
	v_add_f32_e32 v80, v250, v80
	s_waitcnt lgkmcnt(5)
	v_mfma_f32_32x32x16_bf16 v[112:127], v[88:91], v[160:163], v[112:127]
	v_exp_f32_e32 v129, v129
	v_add_f32_e32 v80, v251, v80
	v_exp_f32_e32 v130, v130
	v_add_f32_e32 v80, v198, v80
	v_exp_f32_e32 v131, v131
	v_add_f32_e32 v80, v199, v80
	v_exp_f32_e32 v132, v132
	s_waitcnt lgkmcnt(4)
	v_mfma_f32_32x32x16_bf16 v[96:111], v[92:95], v[160:163], v[96:111]
	v_add_f32_e32 v80, v128, v80
	v_exp_f32_e32 v133, v133
	v_add_f32_e32 v80, v129, v80
	v_exp_f32_e32 v134, v134
	v_add_f32_e32 v80, v130, v80
	v_exp_f32_e32 v135, v135
	v_add_f32_e32 v80, v131, v80
	s_waitcnt lgkmcnt(3)
	v_mfma_f32_32x32x16_bf16 v[112:127], v[220:223], v[156:159], v[112:127]
	v_exp_f32_e32 v136, v136
	v_add_f32_e32 v80, v132, v80
	v_exp_f32_e32 v137, v137
	v_add_f32_e32 v80, v133, v80
	v_exp_f32_e32 v138, v138
	v_add_f32_e32 v80, v134, v80
	v_exp_f32_e32 v139, v139
	s_waitcnt lgkmcnt(2)
	v_mfma_f32_32x32x16_bf16 v[96:111], v[224:227], v[156:159], v[96:111]
	v_add_f32_e32 v80, v135, v80
	v_exp_f32_e32 v140, v140
	v_add_f32_e32 v80, v136, v80
	v_exp_f32_e32 v141, v141
	v_add_f32_e32 v80, v137, v80
	v_exp_f32_e32 v142, v142
	v_add_f32_e32 v80, v138, v80
	s_waitcnt lgkmcnt(1)
	v_mfma_f32_32x32x16_bf16 v[112:127], v[228:231], v[152:155], v[112:127]
	v_exp_f32_e32 v143, v143
	v_add_f32_e32 v80, v139, v80
	v_add_f32_e32 v80, v140, v80
	v_add_f32_e32 v80, v141, v80
	v_add_f32_e32 v80, v142, v80
	v_add_f32_e32 v219, v143, v80
	v_mov_b32_e32 v220, v219
	s_waitcnt lgkmcnt(0)
	v_mfma_f32_32x32x16_bf16 v[96:111], v[240:243], v[152:155], v[96:111]
	v_cvt_pk_bf16_f32 v80, v196, v197
	v_cvt_pk_bf16_f32 v81, v234, v235
	v_cvt_pk_bf16_f32 v82, v237, v238
	v_cvt_pk_bf16_f32 v83, v244, v245
	v_cvt_pk_bf16_f32 v84, v246, v247
	v_cvt_pk_bf16_f32 v85, v248, v249
	v_cvt_pk_bf16_f32 v86, v250, v251
	v_cvt_pk_bf16_f32 v87, v198, v199
	v_cvt_pk_bf16_f32 v88, v128, v129
	v_cvt_pk_bf16_f32 v89, v130, v131
	v_cvt_pk_bf16_f32 v90, v132, v133
	v_cvt_pk_bf16_f32 v91, v134, v135
	v_cvt_pk_bf16_f32 v92, v136, v137
	v_cvt_pk_bf16_f32 v93, v138, v139
	v_cvt_pk_bf16_f32 v94, v140, v141
	v_cvt_pk_bf16_f32 v95, v142, v143
	v_permlane32_swap_b32_e32 v219, v220
	v_permlane32_swap_b32_e32 v80, v82
	v_permlane32_swap_b32_e32 v81, v83
	v_permlane32_swap_b32_e32 v84, v86
	v_permlane32_swap_b32_e32 v85, v87
	v_permlane32_swap_b32_e32 v88, v90
	v_permlane32_swap_b32_e32 v89, v91
	v_permlane32_swap_b32_e32 v92, v94
	v_permlane32_swap_b32_e32 v93, v95
	s_cmp_lt_u32 s50, 61
	s_cselect_b64 s[0:1], -1, 0
	s_cmp_gt_u32 s50, 60
	s_cbranch_scc1 .LBB0_384
	s_add_u32 s74, s70, 0x18e00000
	s_addc_u32 s75, s71, 0
	global_load_dwordx4 v[168:171], v182, s[74:75] offset:2048
	s_add_u32 s74, s70, 0x18e40000
	s_addc_u32 s75, s71, 0
	global_load_dwordx4 v[172:175], v182, s[74:75] offset:2048
	s_add_u32 s74, s72, 0x18e00000
	s_addc_u32 s75, s73, 0
	global_load_dwordx4 v[176:179], v184, s[74:75] offset:1152

; #define SLOAD(i, k0) do { sr_[i].vs0 = *(const GAS bf16x8*)(&Vh[(long)((k0) + sr) * LDK + sc]); sr_[i].vs1 = *(const GAS bf16x8*)(&Vh[(long)((k0) + 32 + sr) * LDK + sc]); \
;     sr_[i].ks0 = *(const GAS bf16x8*)(&Kh[(long)((k0) + kr) * LDK + kc]); } while (0)
; #define SWRITE(b, i) do { *(bf16x8*)(V_lds + (b) * SHM_V + vst0) = sr_[i].vs0; *(bf16x8*)(V_lds + (b) * SHM_V + vst1) = sr_[i].vs1; \
;     *(bf16x8*)(K_lds + (b) * SHM_K + kst) = sr_[i].ks0; } while (0)
; #define RESC(a) do { if (__any((a) < 1.f)) { if (hi == 0) al_l[r32] = (a); asm volatile("s_waitcnt lgkmcnt(0)" ::: "memory"); \
;     _Pragma("unroll") for (int d = 0; d < 4; ++d) _Pragma("unroll") for (int r = 0; r < 16; ++r) o[d][r] *= al_l[crow(r, hi)]; } } while (0)
; template <bool GRPB> __device__ __forceinline__ void attn_pass(const float mbK, const float bmax2, const int pass, float* __restrict__ scr, bf16* __restrict__ mixrow, const float lam, const float* __restrict__ gsub, const float one_m_li, ...
;     ...
;   for (int t = 1; t + 1 < NT; t += 2) {
;     HSTEP(pB0, pB1, mnB, alB, pA0, pA1, alA, t * KVBLK, SLOAD(0, (t + 2) * KVBLK));
;     __syncthreads(); SWRITE(bm1, 0);
;     RESC(alB);
;     { const int tmp = bm1; bm1 = b0; b0 = bp1; bp1 = tmp; }
;     HSTEP(pA0, pA1, mnA, alA, pB0, pB1, alB, (t + 1) * KVBLK, if (t + 3 < NT) SLOAD(0, (t + 3) * KVBLK));
;     __syncthreads(); if (t + 3 < NT) SWRITE(bm1, 0);
;     RESC(alA);
;     { const int tmp = bm1; bm1 = b0; b0 = bp1; bp1 = tmp; }
.LBB0_388:
	s_andn2_b64 vcc, exec, s[0:1]
	s_mov_b64 s[0:1], -1
	s_barrier
	s_cbranch_vccnz .LBB0_390
	s_add_i32 s0, s4, 0
	v_add_u32_e32 v97, s0, v194
	v_add_u32_e32 v98, s0, v193
	s_add_u32 s70, s70, s16
	s_addc_u32 s71, s71, s17
	s_add_u32 s72, s72, s16
	s_addc_u32 s73, s73, s17
	s_addk_i32 s48, 0x80
	v_add_u32_e32 v216, 0x200, v216
	s_add_i32 s50, s50, 2
	s_mov_b64 s[0:1], 0
	v_add_u32_e32 v96, s36, v195
	s_waitcnt vmcnt(2)
	ds_write_b128 v98, v[168:171]
	s_waitcnt vmcnt(1)
	ds_write_b128 v97, v[172:175]
	s_waitcnt vmcnt(0)
	ds_write_b128 v96, v[176:179] offset:49152
